# out-proj / FFN gate-up / FFN down K-loops: s_nop pads so every 16-MFMA block starts on an 8-byte boundary
# speedup vs baseline: 1.0077x; 1.0077x over previous
; #define LDA(dst, b, h) for (int m = 0; m < 4; ++m) for (int k = 0; k < 2; ++k) \
;     dst[m][k] = *reinterpret_cast<const bf16x8*>((char*)SA(b, h) + lds_byte(wr * 64 + m * 16 + fr, k * 32 + fq * 8))
; #define LDB(dst, b, h) for (int n = 0; n < 2; ++n) for (int k = 0; k < 2; ++k) \
;     dst[n][k] = *reinterpret_cast<const bf16x8*>((char*)SB(b, h) + lds_byte(wc * 32 + n * 16 + fr, k * 32 + fq * 8))
; #define MMA(ai, bj, At, Bq) do { __builtin_amdgcn_s_setprio(1); \
;     for (int m = 0; m < 4; ++m) for (int n = 0; n < 2; ++n) for (int k = 0; k < 2; ++k) \
;       acc[ai][bj][m][n] = __builtin_amdgcn_mfma_f32_16x16x32_bf16(At[m][k], Bq[n][k], acc[ai][bj][m][n], 0, 0, 0); \
;     __builtin_amdgcn_s_setprio(0); } while (0)
; #define WAIT_L(n) asm volatile("s_waitcnt lgkmcnt(" #n ")" ::: "memory")
; #define BAR __builtin_amdgcn_s_barrier()
; #define SCHED __builtin_amdgcn_sched_barrier(0)
; template <class Epi>
; __device__ __forceinline__ void gemm_tile(const u16* __restrict__ A, const u16* __restrict__ Bt, int K,
;                                           int brow, int bcol, bool first, bool has_next, int nbrow, int nbcol, Epi epi) {
;     ...
;     LDB(B0, 0, 0); SCHED; LDA(At, 0, 0); STAGE(SA(1, 1), A, brow + HALF, t + 1);
;     WAIT_L(8); BAR; WAIT_L(0); MMA(0, 0, At, B0); BAR; SCHED;
;     LDB(B1, 0, 1); STAGE(SB(0, 0), Bt, bcol, t + 2);
;     BAR; WAIT_L(0); MMA(0, 1, At, B1); BAR;
;     LDA(At, 0, 1); STAGE(SA(0, 0), A, brow, t + 2);
;     BAR; WAIT_L(0); MMA(1, 0, At, B0); BAR; SCHED;
.LBB0_457:
	ds_read_b128 v[166:169], v164
	ds_read_b128 v[176:179], v164 offset:1024
	ds_read_b128 v[180:183], v164 offset:2048
	ds_read_b128 v[184:187], v164 offset:3072
	v_add_u32_e32 v173, 0xc000, v153
	v_lshl_add_u64 v[170:171], s[28:29], 0, v[144:145]
	v_readfirstlane_b32 s3, v173
	v_lshl_add_u64 v[174:175], v[170:171], 0, s[4:5]
	s_mov_b32 m0, s3
	ds_read_b128 v[188:191], v159
	ds_read_b128 v[192:195], v159 offset:1024
	ds_read_b128 v[196:199], v158
	ds_read_b128 v[200:203], v158 offset:1024
	ds_read_b128 v[204:207], v157
	ds_read_b128 v[208:211], v157 offset:1024
	ds_read_b128 v[212:215], v156
	ds_read_b128 v[216:219], v156 offset:1024
	global_load_lds_dwordx4 v[174:175], off
	v_add_u32_e32 v174, 0xe000, v153
	v_lshl_add_u64 v[236:237], s[28:29], 0, v[146:147]
	v_readfirstlane_b32 s3, v174
	v_lshl_add_u64 v[220:221], v[236:237], 0, s[4:5]
	s_mov_b32 m0, s3
	s_nop 0
	global_load_lds_dwordx4 v[220:221], off
	s_waitcnt lgkmcnt(8)
	s_barrier
	s_waitcnt lgkmcnt(0)
	s_setprio 1
	s_waitcnt lgkmcnt(0)
	s_nop 0
	v_mfma_f32_16x16x32_bf16 v[124:127], v[188:191], v[166:169], v[124:127]
	v_mfma_f32_16x16x32_bf16 v[120:123], v[188:191], v[180:183], v[120:123]
	v_mfma_f32_16x16x32_bf16 v[116:119], v[196:199], v[166:169], v[116:119]
	v_mfma_f32_16x16x32_bf16 v[112:115], v[196:199], v[180:183], v[112:115]
	v_mfma_f32_16x16x32_bf16 v[108:111], v[204:207], v[166:169], v[108:111]
	v_mfma_f32_16x16x32_bf16 v[104:107], v[204:207], v[180:183], v[104:107]
	v_mfma_f32_16x16x32_bf16 v[100:103], v[212:215], v[166:169], v[100:103]
	v_mfma_f32_16x16x32_bf16 v[96:99], v[212:215], v[180:183], v[96:99]
	v_mfma_f32_16x16x32_bf16 v[124:127], v[192:195], v[176:179], v[124:127]
	v_mfma_f32_16x16x32_bf16 v[120:123], v[192:195], v[184:187], v[120:123]
	v_mfma_f32_16x16x32_bf16 v[116:119], v[200:203], v[176:179], v[116:119]
	v_mfma_f32_16x16x32_bf16 v[112:115], v[200:203], v[184:187], v[112:115]
	v_mfma_f32_16x16x32_bf16 v[108:111], v[208:211], v[176:179], v[108:111]
	v_mfma_f32_16x16x32_bf16 v[104:107], v[208:211], v[184:187], v[104:107]
	v_mfma_f32_16x16x32_bf16 v[100:103], v[216:219], v[176:179], v[100:103]
	v_mfma_f32_16x16x32_bf16 v[96:99], v[216:219], v[184:187], v[96:99]
	s_setprio 0
	s_barrier
	v_lshl_add_u64 v[240:241], s[28:29], 0, v[132:133]
	v_readfirstlane_b32 s3, v154
	v_add_u32_e32 v165, 0x2000, v154
	v_lshl_add_u64 v[238:239], v[240:241], 0, s[10:11]
	s_mov_b32 m0, s3
	v_lshl_add_u64 v[242:243], s[28:29], 0, v[134:135]
	v_readfirstlane_b32 s3, v165
	ds_read_b128 v[220:223], v163
	ds_read_b128 v[224:227], v163 offset:1024
	ds_read_b128 v[228:231], v163 offset:2048
	ds_read_b128 v[232:235], v163 offset:3072
	global_load_lds_dwordx4 v[238:239], off
	v_lshl_add_u64 v[238:239], v[242:243], 0, s[10:11]
	s_mov_b32 m0, s3
	s_nop 0
	global_load_lds_dwordx4 v[238:239], off
	s_barrier
	s_waitcnt lgkmcnt(0)
	s_setprio 1
	s_waitcnt lgkmcnt(0)
	s_nop 0
	v_mfma_f32_16x16x32_bf16 v[92:95], v[188:191], v[220:223], v[92:95]
	v_mfma_f32_16x16x32_bf16 v[88:91], v[188:191], v[228:231], v[88:91]
	v_mfma_f32_16x16x32_bf16 v[84:87], v[196:199], v[220:223], v[84:87]
	v_mfma_f32_16x16x32_bf16 v[80:83], v[196:199], v[228:231], v[80:83]
	v_mfma_f32_16x16x32_bf16 v[76:79], v[204:207], v[220:223], v[76:79]
	v_mfma_f32_16x16x32_bf16 v[72:75], v[204:207], v[228:231], v[72:75]
	v_mfma_f32_16x16x32_bf16 v[68:71], v[212:215], v[220:223], v[68:71]
	v_mfma_f32_16x16x32_bf16 v[64:67], v[212:215], v[228:231], v[64:67]
	v_mfma_f32_16x16x32_bf16 v[92:95], v[192:195], v[224:227], v[92:95]
	v_mfma_f32_16x16x32_bf16 v[88:91], v[192:195], v[232:235], v[88:91]
	v_mfma_f32_16x16x32_bf16 v[84:87], v[200:203], v[224:227], v[84:87]
	v_mfma_f32_16x16x32_bf16 v[80:83], v[200:203], v[232:235], v[80:83]
	v_mfma_f32_16x16x32_bf16 v[76:79], v[208:211], v[224:227], v[76:79]
	v_mfma_f32_16x16x32_bf16 v[72:75], v[208:211], v[232:235], v[72:75]
	v_mfma_f32_16x16x32_bf16 v[68:71], v[216:219], v[224:227], v[68:71]
	v_mfma_f32_16x16x32_bf16 v[64:67], v[216:219], v[232:235], v[64:67]
	s_setprio 0
	v_lshl_add_u64 v[244:245], s[28:29], 0, v[136:137]
	v_readfirstlane_b32 s3, v153
	v_lshl_add_u64 v[238:239], v[244:245], 0, s[12:13]
	s_mov_b32 m0, s3
	v_lshl_add_u64 v[246:247], s[28:29], 0, v[138:139]
	v_readfirstlane_b32 s3, v152
	s_barrier
	ds_read_b128 v[188:191], v159 offset:16384
	ds_read_b128 v[192:195], v159 offset:17408
	ds_read_b128 v[196:199], v158 offset:16384
	ds_read_b128 v[200:203], v158 offset:17408
	ds_read_b128 v[204:207], v157 offset:16384
	ds_read_b128 v[208:211], v157 offset:17408
	ds_read_b128 v[212:215], v156 offset:16384
	ds_read_b128 v[216:219], v156 offset:17408
	global_load_lds_dwordx4 v[238:239], off
	v_lshl_add_u64 v[238:239], v[246:247], 0, s[12:13]
	s_mov_b32 m0, s3
	s_nop 0
	global_load_lds_dwordx4 v[238:239], off
	s_barrier
	s_waitcnt lgkmcnt(0)
	s_setprio 1
	s_waitcnt lgkmcnt(0)
	s_nop 0
	v_mfma_f32_16x16x32_bf16 v[60:63], v[188:191], v[166:169], v[60:63]
	v_mfma_f32_16x16x32_bf16 v[56:59], v[188:191], v[180:183], v[56:59]
	v_mfma_f32_16x16x32_bf16 v[52:55], v[196:199], v[166:169], v[52:55]
	v_mfma_f32_16x16x32_bf16 v[48:51], v[196:199], v[180:183], v[48:51]
	v_mfma_f32_16x16x32_bf16 v[44:47], v[204:207], v[166:169], v[44:47]
	v_mfma_f32_16x16x32_bf16 v[40:43], v[204:207], v[180:183], v[40:43]
	v_mfma_f32_16x16x32_bf16 v[36:39], v[212:215], v[166:169], v[36:39]
	v_mfma_f32_16x16x32_bf16 v[32:35], v[212:215], v[180:183], v[32:35]
	v_mfma_f32_16x16x32_bf16 v[60:63], v[192:195], v[176:179], v[60:63]
	v_mfma_f32_16x16x32_bf16 v[56:59], v[192:195], v[184:187], v[56:59]
	v_mfma_f32_16x16x32_bf16 v[52:55], v[200:203], v[176:179], v[52:55]
	v_mfma_f32_16x16x32_bf16 v[48:51], v[200:203], v[184:187], v[48:51]
	v_mfma_f32_16x16x32_bf16 v[44:47], v[208:211], v[176:179], v[44:47]
	v_mfma_f32_16x16x32_bf16 v[40:43], v[208:211], v[184:187], v[40:43]
	v_mfma_f32_16x16x32_bf16 v[36:39], v[216:219], v[176:179], v[36:39]
	v_mfma_f32_16x16x32_bf16 v[32:35], v[216:219], v[184:187], v[32:35]
	s_setprio 0
	s_barrier
; #define LDA(dst, b, h) for (int m = 0; m < 4; ++m) for (int k = 0; k < 2; ++k) \
;     dst[m][k] = *reinterpret_cast<const bf16x8*>((char*)SA(b, h) + lds_byte(wr * 64 + m * 16 + fr, k * 32 + fq * 8))
; #define LDB(dst, b, h) for (int n = 0; n < 2; ++n) for (int k = 0; k < 2; ++k) \
;     dst[n][k] = *reinterpret_cast<const bf16x8*>((char*)SB(b, h) + lds_byte(wc * 32 + n * 16 + fr, k * 32 + fq * 8))
; #define MMA(ai, bj, At, Bq) do { __builtin_amdgcn_s_setprio(1); \
;     for (int m = 0; m < 4; ++m) for (int n = 0; n < 2; ++n) for (int k = 0; k < 2; ++k) \
;       acc[ai][bj][m][n] = __builtin_amdgcn_mfma_f32_16x16x32_bf16(At[m][k], Bq[n][k], acc[ai][bj][m][n], 0, 0, 0); \
;     __builtin_amdgcn_s_setprio(0); } while (0)
; #define WAIT_V(n) asm volatile("s_waitcnt vmcnt(" #n ")" ::: "memory")
; #define WAIT_L(n) asm volatile("s_waitcnt lgkmcnt(" #n ")" ::: "memory")
; #define BAR __builtin_amdgcn_s_barrier()
; #define SCHED __builtin_amdgcn_sched_barrier(0)
; template <class Epi>
; __device__ __forceinline__ void gemm_tile(const u16* __restrict__ A, const u16* __restrict__ Bt, int K,
;                                           int brow, int bcol, bool first, bool has_next, int nbrow, int nbcol, Epi epi) {
;     ...
;     STAGE(SB(0, 1), Bt, bcol + HALF, t + 2);
;     WAIT_V(6); BAR; MMA(1, 1, At, B1); BAR;
;     LDB(B0, 1, 0); SCHED; LDA(At, 1, 0); STAGE(SA(0, 1), A, brow + HALF, t + 2);
;     WAIT_L(8); BAR; WAIT_L(0); MMA(0, 0, At, B0); BAR; SCHED;
;     LDB(B1, 1, 1); STAGE(SB(1, 0), Bt, bcol, t + 3);
;     BAR; WAIT_L(0); MMA(0, 1, At, B1); BAR;
;     LDA(At, 1, 1); STAGE(SA(1, 0), A, brow, t + 3);
	v_lshl_add_u64 v[248:249], s[28:29], 0, v[140:141]
	v_readfirstlane_b32 s3, v151
	v_lshl_add_u64 v[166:167], v[248:249], 0, s[10:11]
	s_mov_b32 m0, s3
	v_lshl_add_u64 v[250:251], s[28:29], 0, v[142:143]
	global_load_lds_dwordx4 v[166:167], off
	v_add_u32_e32 v166, 0x2000, v151
	v_lshl_add_u64 v[168:169], v[250:251], 0, s[10:11]
	v_readfirstlane_b32 s3, v166
	s_mov_b32 m0, s3
	s_nop 0
	global_load_lds_dwordx4 v[168:169], off
	s_waitcnt vmcnt(6)
	s_barrier
	s_setprio 1
	v_mfma_f32_16x16x32_bf16 v[28:31], v[188:191], v[220:223], v[28:31]
	v_mfma_f32_16x16x32_bf16 v[24:27], v[188:191], v[228:231], v[24:27]
	v_mfma_f32_16x16x32_bf16 v[20:23], v[196:199], v[220:223], v[20:23]
	v_mfma_f32_16x16x32_bf16 v[16:19], v[196:199], v[228:231], v[16:19]
	v_mfma_f32_16x16x32_bf16 v[12:15], v[204:207], v[220:223], v[12:15]
	v_mfma_f32_16x16x32_bf16 v[8:11], v[204:207], v[228:231], v[8:11]
	v_mfma_f32_16x16x32_bf16 v[4:7], v[212:215], v[220:223], v[4:7]
	v_mfma_f32_16x16x32_bf16 v[0:3], v[212:215], v[228:231], v[0:3]
	v_mfma_f32_16x16x32_bf16 v[28:31], v[192:195], v[224:227], v[28:31]
	v_mfma_f32_16x16x32_bf16 v[24:27], v[192:195], v[232:235], v[24:27]
	v_mfma_f32_16x16x32_bf16 v[20:23], v[200:203], v[224:227], v[20:23]
	v_mfma_f32_16x16x32_bf16 v[16:19], v[200:203], v[232:235], v[16:19]
	v_mfma_f32_16x16x32_bf16 v[12:15], v[208:211], v[224:227], v[12:15]
	v_mfma_f32_16x16x32_bf16 v[8:11], v[208:211], v[232:235], v[8:11]
	v_mfma_f32_16x16x32_bf16 v[4:7], v[216:219], v[224:227], v[4:7]
	v_mfma_f32_16x16x32_bf16 v[0:3], v[216:219], v[232:235], v[0:3]
	s_setprio 0
	s_barrier
	ds_read_b128 v[176:179], v162
	ds_read_b128 v[180:183], v162 offset:1024
	ds_read_b128 v[184:187], v162 offset:2048
	ds_read_b128 v[188:191], v162 offset:3072
	v_readfirstlane_b32 s3, v150
	v_lshl_add_u64 v[168:169], v[170:171], 0, s[12:13]
	s_mov_b32 m0, s3
	v_readfirstlane_b32 s3, v149
	ds_read_b128 v[192:195], v159 offset:32768
	ds_read_b128 v[196:199], v159 offset:33792
	ds_read_b128 v[200:203], v158 offset:32768
	ds_read_b128 v[204:207], v158 offset:33792
	ds_read_b128 v[208:211], v157 offset:32768
	ds_read_b128 v[212:215], v157 offset:33792
	ds_read_b128 v[216:219], v156 offset:32768
	ds_read_b128 v[220:223], v156 offset:33792
	global_load_lds_dwordx4 v[168:169], off
	v_lshl_add_u64 v[168:169], v[236:237], 0, s[12:13]
	s_mov_b32 m0, s3
	s_nop 0
	global_load_lds_dwordx4 v[168:169], off
	s_waitcnt lgkmcnt(8)
	s_barrier
	s_waitcnt lgkmcnt(0)
	s_setprio 1
	s_waitcnt lgkmcnt(0)
	v_mfma_f32_16x16x32_bf16 v[124:127], v[192:195], v[176:179], v[124:127]
	v_mfma_f32_16x16x32_bf16 v[120:123], v[192:195], v[184:187], v[120:123]
	v_mfma_f32_16x16x32_bf16 v[116:119], v[200:203], v[176:179], v[116:119]
	v_mfma_f32_16x16x32_bf16 v[112:115], v[200:203], v[184:187], v[112:115]
	v_mfma_f32_16x16x32_bf16 v[108:111], v[208:211], v[176:179], v[108:111]
	v_mfma_f32_16x16x32_bf16 v[104:107], v[208:211], v[184:187], v[104:107]
	v_mfma_f32_16x16x32_bf16 v[100:103], v[216:219], v[176:179], v[100:103]
	v_mfma_f32_16x16x32_bf16 v[96:99], v[216:219], v[184:187], v[96:99]
	v_mfma_f32_16x16x32_bf16 v[124:127], v[196:199], v[180:183], v[124:127]
	v_mfma_f32_16x16x32_bf16 v[120:123], v[196:199], v[188:191], v[120:123]
	v_mfma_f32_16x16x32_bf16 v[116:119], v[204:207], v[180:183], v[116:119]
	v_mfma_f32_16x16x32_bf16 v[112:115], v[204:207], v[188:191], v[112:115]
	v_mfma_f32_16x16x32_bf16 v[108:111], v[212:215], v[180:183], v[108:111]
	v_mfma_f32_16x16x32_bf16 v[104:107], v[212:215], v[188:191], v[104:107]
	v_mfma_f32_16x16x32_bf16 v[100:103], v[220:223], v[180:183], v[100:103]
	v_mfma_f32_16x16x32_bf16 v[96:99], v[220:223], v[188:191], v[96:99]
	s_setprio 0
	s_barrier
	v_add_u32_e32 v167, s84, v155
	v_lshl_add_u64 v[168:169], v[240:241], 0, s[14:15]
	v_readfirstlane_b32 s3, v167
	s_mov_b32 m0, s3
	ds_read_b128 v[224:227], v161
	ds_read_b128 v[228:231], v161 offset:1024
	ds_read_b128 v[232:235], v161 offset:2048
	ds_read_b128 v[236:239], v161 offset:3072
	global_load_lds_dwordx4 v[168:169], off
	v_add_u32_e32 v168, 0x2000, v167
	v_lshl_add_u64 v[170:171], v[242:243], 0, s[14:15]
	v_readfirstlane_b32 s3, v168
	s_mov_b32 m0, s3
	s_nop 0
	global_load_lds_dwordx4 v[170:171], off
	s_barrier
	s_waitcnt lgkmcnt(0)
	s_setprio 1
	s_waitcnt lgkmcnt(0)
	v_mfma_f32_16x16x32_bf16 v[92:95], v[192:195], v[224:227], v[92:95]
	v_mfma_f32_16x16x32_bf16 v[88:91], v[192:195], v[232:235], v[88:91]
	v_mfma_f32_16x16x32_bf16 v[84:87], v[200:203], v[224:227], v[84:87]
	v_mfma_f32_16x16x32_bf16 v[80:83], v[200:203], v[232:235], v[80:83]
	v_mfma_f32_16x16x32_bf16 v[76:79], v[208:211], v[224:227], v[76:79]
	v_mfma_f32_16x16x32_bf16 v[72:75], v[208:211], v[232:235], v[72:75]
	v_mfma_f32_16x16x32_bf16 v[68:71], v[216:219], v[224:227], v[68:71]
	v_mfma_f32_16x16x32_bf16 v[64:67], v[216:219], v[232:235], v[64:67]
	v_mfma_f32_16x16x32_bf16 v[92:95], v[196:199], v[228:231], v[92:95]
	v_mfma_f32_16x16x32_bf16 v[88:91], v[196:199], v[236:239], v[88:91]
	v_mfma_f32_16x16x32_bf16 v[84:87], v[204:207], v[228:231], v[84:87]
	v_mfma_f32_16x16x32_bf16 v[80:83], v[204:207], v[236:239], v[80:83]
	v_mfma_f32_16x16x32_bf16 v[76:79], v[212:215], v[228:231], v[76:79]
	v_mfma_f32_16x16x32_bf16 v[72:75], v[212:215], v[236:239], v[72:75]
	v_mfma_f32_16x16x32_bf16 v[68:71], v[220:223], v[228:231], v[68:71]
	v_mfma_f32_16x16x32_bf16 v[64:67], v[220:223], v[236:239], v[64:67]
	s_setprio 0
	v_add_u32_e32 v169, 0x8000, v153
	v_lshl_add_u64 v[170:171], v[244:245], 0, s[16:17]
	v_readfirstlane_b32 s3, v169
	s_mov_b32 m0, s3
	s_barrier
; #define LDA(dst, b, h) for (int m = 0; m < 4; ++m) for (int k = 0; k < 2; ++k) \
;     dst[m][k] = *reinterpret_cast<const bf16x8*>((char*)SA(b, h) + lds_byte(wr * 64 + m * 16 + fr, k * 32 + fq * 8))
; #define LDB(dst, b, h) for (int n = 0; n < 2; ++n) for (int k = 0; k < 2; ++k) \
;     dst[n][k] = *reinterpret_cast<const bf16x8*>((char*)SB(b, h) + lds_byte(wc * 32 + n * 16 + fr, k * 32 + fq * 8))
; #define MMA(ai, bj, At, Bq) do { __builtin_amdgcn_s_setprio(1); \
;     for (int m = 0; m < 4; ++m) for (int n = 0; n < 2; ++n) for (int k = 0; k < 2; ++k) \
;       acc[ai][bj][m][n] = __builtin_amdgcn_mfma_f32_16x16x32_bf16(At[m][k], Bq[n][k], acc[ai][bj][m][n], 0, 0, 0); \
;     __builtin_amdgcn_s_setprio(0); } while (0)
; #define WAIT_V(n) asm volatile("s_waitcnt vmcnt(" #n ")" ::: "memory")
; #define WAIT_L(n) asm volatile("s_waitcnt lgkmcnt(" #n ")" ::: "memory")
; #define BAR __builtin_amdgcn_s_barrier()
; #define SCHED __builtin_amdgcn_sched_barrier(0)
; template <class Epi>
; __device__ __forceinline__ void gemm_tile(const u16* __restrict__ A, const u16* __restrict__ Bt, int K,
;                                           int brow, int bcol, bool first, bool has_next, int nbrow, int nbcol, Epi epi) {
;     ...
;     LDA(At, 1, 1); STAGE(SA(1, 0), A, brow, t + 3);
;     BAR; WAIT_L(0); MMA(1, 0, At, B0); BAR; SCHED;
;     STAGE(SB(1, 1), Bt, bcol + HALF, t + 3);
;     WAIT_V(6); BAR; MMA(1, 1, At, B1); BAR;
;   }
;   { LDB(B0, 0, 0); LDA(At, 0, 0); STAGE(SA(1, 1), A, brow + HALF, nt - 1);
;     BAR; WAIT_L(0); MMA(0, 0, At, B0); BAR;
	ds_read_b128 v[192:195], v159 offset:49152
	ds_read_b128 v[196:199], v159 offset:50176
	ds_read_b128 v[200:203], v158 offset:49152
	ds_read_b128 v[204:207], v158 offset:50176
	ds_read_b128 v[208:211], v157 offset:49152
	ds_read_b128 v[212:215], v157 offset:50176
	ds_read_b128 v[216:219], v156 offset:49152
	ds_read_b128 v[220:223], v156 offset:50176
	global_load_lds_dwordx4 v[170:171], off
	v_add_u32_e32 v170, 0xa000, v153
	v_lshl_add_u64 v[240:241], v[246:247], 0, s[16:17]
	v_readfirstlane_b32 s3, v170
	s_mov_b32 m0, s3
	s_nop 0
	global_load_lds_dwordx4 v[240:241], off
	s_barrier
	s_waitcnt lgkmcnt(0)
	s_setprio 1
	s_waitcnt lgkmcnt(0)
	s_nop 0
	v_mfma_f32_16x16x32_bf16 v[60:63], v[192:195], v[176:179], v[60:63]
	v_mfma_f32_16x16x32_bf16 v[56:59], v[192:195], v[184:187], v[56:59]
	v_mfma_f32_16x16x32_bf16 v[52:55], v[200:203], v[176:179], v[52:55]
	v_mfma_f32_16x16x32_bf16 v[48:51], v[200:203], v[184:187], v[48:51]
	v_mfma_f32_16x16x32_bf16 v[44:47], v[208:211], v[176:179], v[44:47]
	v_mfma_f32_16x16x32_bf16 v[40:43], v[208:211], v[184:187], v[40:43]
	v_mfma_f32_16x16x32_bf16 v[36:39], v[216:219], v[176:179], v[36:39]
	v_mfma_f32_16x16x32_bf16 v[32:35], v[216:219], v[184:187], v[32:35]
	v_mfma_f32_16x16x32_bf16 v[60:63], v[196:199], v[180:183], v[60:63]
	v_mfma_f32_16x16x32_bf16 v[56:59], v[196:199], v[188:191], v[56:59]
	v_mfma_f32_16x16x32_bf16 v[52:55], v[204:207], v[180:183], v[52:55]
	v_mfma_f32_16x16x32_bf16 v[48:51], v[204:207], v[188:191], v[48:51]
	v_mfma_f32_16x16x32_bf16 v[44:47], v[212:215], v[180:183], v[44:47]
	v_mfma_f32_16x16x32_bf16 v[40:43], v[212:215], v[188:191], v[40:43]
	v_mfma_f32_16x16x32_bf16 v[36:39], v[220:223], v[180:183], v[36:39]
	v_mfma_f32_16x16x32_bf16 v[32:35], v[220:223], v[188:191], v[32:35]
	s_setprio 0
	s_barrier
	v_add_u32_e32 v171, s85, v155
	v_add_u32_e32 v172, 0x2000, v171
	v_readfirstlane_b32 s3, v171
	v_lshl_add_u64 v[176:177], v[248:249], 0, s[14:15]
	s_mov_b32 m0, s3
	v_readfirstlane_b32 s3, v172
	global_load_lds_dwordx4 v[176:177], off
	v_lshl_add_u64 v[176:177], v[250:251], 0, s[14:15]
	s_mov_b32 m0, s3
	s_nop 0
	global_load_lds_dwordx4 v[176:177], off
	s_waitcnt vmcnt(6)
	s_barrier
	s_setprio 1
	s_nop 0
	v_mfma_f32_16x16x32_bf16 v[28:31], v[192:195], v[224:227], v[28:31]
	v_mfma_f32_16x16x32_bf16 v[24:27], v[192:195], v[232:235], v[24:27]
	v_mfma_f32_16x16x32_bf16 v[20:23], v[200:203], v[224:227], v[20:23]
	v_mfma_f32_16x16x32_bf16 v[16:19], v[200:203], v[232:235], v[16:19]
	v_mfma_f32_16x16x32_bf16 v[12:15], v[208:211], v[224:227], v[12:15]
	v_mfma_f32_16x16x32_bf16 v[8:11], v[208:211], v[232:235], v[8:11]
	v_mfma_f32_16x16x32_bf16 v[4:7], v[216:219], v[224:227], v[4:7]
	v_mfma_f32_16x16x32_bf16 v[0:3], v[216:219], v[232:235], v[0:3]
	v_mfma_f32_16x16x32_bf16 v[28:31], v[196:199], v[228:231], v[28:31]
	v_mfma_f32_16x16x32_bf16 v[24:27], v[196:199], v[236:239], v[24:27]
	v_mfma_f32_16x16x32_bf16 v[20:23], v[204:207], v[228:231], v[20:23]
	v_mfma_f32_16x16x32_bf16 v[16:19], v[204:207], v[236:239], v[16:19]
	v_mfma_f32_16x16x32_bf16 v[12:15], v[212:215], v[228:231], v[12:15]
	v_mfma_f32_16x16x32_bf16 v[8:11], v[212:215], v[236:239], v[8:11]
	v_mfma_f32_16x16x32_bf16 v[4:7], v[220:223], v[228:231], v[4:7]
	v_mfma_f32_16x16x32_bf16 v[0:3], v[220:223], v[236:239], v[0:3]
	s_setprio 0
	s_add_i32 s1, s1, 2
	s_add_u32 s28, s28, 0x100
	s_addc_u32 s29, s29, 0
	s_cmp_lt_u32 s1, 12
	s_barrier
	s_nop 0
	s_cbranch_scc1 .LBB0_457
	s_add_u32 s26, s34, s26
	s_addc_u32 s27, s35, s27
	v_lshl_add_u64 v[208:209], s[26:27], 0, v[128:129]
	v_readfirstlane_b32 s1, v173
	v_lshl_add_u64 v[208:209], v[208:209], 0, s[18:19]
	s_mov_b32 m0, s1
	ds_read_b128 v[132:135], v164
	ds_read_b128 v[136:139], v164 offset:1024
	ds_read_b128 v[140:143], v164 offset:2048
	ds_read_b128 v[144:147], v164 offset:3072
	ds_read_b128 v[176:179], v159
	ds_read_b128 v[180:183], v159 offset:1024
	ds_read_b128 v[184:187], v158
	ds_read_b128 v[188:191], v158 offset:1024
	ds_read_b128 v[192:195], v157
	ds_read_b128 v[196:199], v157 offset:1024
	ds_read_b128 v[200:203], v156
	ds_read_b128 v[204:207], v156 offset:1024
	global_load_lds_dwordx4 v[208:209], off
	v_lshl_add_u64 v[208:209], s[26:27], 0, v[130:131]
	v_readfirstlane_b32 s1, v174
	v_lshl_add_u64 v[208:209], v[208:209], 0, s[18:19]
	s_mov_b32 m0, s1
	s_nop 0
	global_load_lds_dwordx4 v[208:209], off
	s_barrier
	s_waitcnt lgkmcnt(0)
	s_setprio 1
	s_waitcnt lgkmcnt(0)
	v_mfma_f32_16x16x32_bf16 v[124:127], v[176:179], v[132:135], v[124:127]
	v_mfma_f32_16x16x32_bf16 v[120:123], v[176:179], v[140:143], v[120:123]
	v_mfma_f32_16x16x32_bf16 v[116:119], v[184:187], v[132:135], v[116:119]
	v_mfma_f32_16x16x32_bf16 v[112:115], v[184:187], v[140:143], v[112:115]
	v_mfma_f32_16x16x32_bf16 v[100:103], v[200:203], v[132:135], v[100:103]
	v_mfma_f32_16x16x32_bf16 v[96:99], v[200:203], v[140:143], v[96:99]
	v_mfma_f32_16x16x32_bf16 v[124:127], v[180:183], v[136:139], v[124:127]
	v_mfma_f32_16x16x32_bf16 v[120:123], v[180:183], v[144:147], v[120:123]
	v_mfma_f32_16x16x32_bf16 v[116:119], v[188:191], v[136:139], v[116:119]
	v_mfma_f32_16x16x32_bf16 v[112:115], v[188:191], v[144:147], v[112:115]
	v_mfma_f32_16x16x32_bf16 v[108:111], v[192:195], v[132:135], v[108:111]
	v_mfma_f32_16x16x32_bf16 v[104:107], v[192:195], v[140:143], v[104:107]
	v_mfma_f32_16x16x32_bf16 v[100:103], v[204:207], v[136:139], v[100:103]
	v_mfma_f32_16x16x32_bf16 v[96:99], v[204:207], v[144:147], v[96:99]
	v_mfma_f32_16x16x32_bf16 v[208:211], v[196:199], v[136:139], v[108:111]
	v_mfma_f32_16x16x32_bf16 v[212:215], v[196:199], v[144:147], v[104:107]
	s_setprio 0
	s_barrier
; #define LDA(dst, b, h) for (int m = 0; m < 4; ++m) for (int k = 0; k < 2; ++k) \
;     dst[m][k] = *reinterpret_cast<const bf16x8*>((char*)SA(b, h) + lds_byte(wr * 64 + m * 16 + fr, k * 32 + fq * 8))
; #define LDB(dst, b, h) for (int n = 0; n < 2; ++n) for (int k = 0; k < 2; ++k) \
;     dst[n][k] = *reinterpret_cast<const bf16x8*>((char*)SB(b, h) + lds_byte(wc * 32 + n * 16 + fr, k * 32 + fq * 8))
; #define MMA(ai, bj, At, Bq) do { __builtin_amdgcn_s_setprio(1); \
;     for (int m = 0; m < 4; ++m) for (int n = 0; n < 2; ++n) for (int k = 0; k < 2; ++k) \
;       acc[ai][bj][m][n] = __builtin_amdgcn_mfma_f32_16x16x32_bf16(At[m][k], Bq[n][k], acc[ai][bj][m][n], 0, 0, 0); \
;     __builtin_amdgcn_s_setprio(0); } while (0)
; #define WAIT_V(n) asm volatile("s_waitcnt vmcnt(" #n ")" ::: "memory")
; #define WAIT_L(n) asm volatile("s_waitcnt lgkmcnt(" #n ")" ::: "memory")
; #define BAR __builtin_amdgcn_s_barrier()
; template <class Epi>
; __device__ __forceinline__ void gemm_tile(const u16* __restrict__ A, const u16* __restrict__ Bt, int K,
;                                           int brow, int bcol, bool first, bool has_next, int nbrow, int nbcol, Epi epi) {
;     ...
;     LDB(B1, 0, 1); BAR; WAIT_L(0); MMA(0, 1, At, B1); BAR;
;     LDA(At, 0, 1); WAIT_V(4); BAR; WAIT_L(0); MMA(1, 0, At, B0); MMA(1, 1, At, B1); BAR; }
;   { LDB(B0, 1, 0); LDA(At, 1, 0); WAIT_V(2); BAR; WAIT_L(0); MMA(0, 0, At, B0); BAR;
	s_nop 1
	ds_read_b128 v[104:107], v163
	ds_read_b128 v[108:111], v163 offset:1024
	ds_read_b128 v[216:219], v163 offset:2048
	ds_read_b128 v[220:223], v163 offset:3072
	s_barrier
	s_waitcnt lgkmcnt(0)
	s_setprio 1
	s_waitcnt lgkmcnt(0)
	v_mfma_f32_16x16x32_bf16 v[84:87], v[184:187], v[104:107], v[84:87]
	v_mfma_f32_16x16x32_bf16 v[80:83], v[184:187], v[216:219], v[80:83]
	v_mfma_f32_16x16x32_bf16 v[68:71], v[200:203], v[104:107], v[68:71]
	v_mfma_f32_16x16x32_bf16 v[64:67], v[200:203], v[216:219], v[64:67]
	v_mfma_f32_16x16x32_bf16 v[92:95], v[176:179], v[104:107], v[92:95]
	v_mfma_f32_16x16x32_bf16 v[88:91], v[176:179], v[216:219], v[88:91]
	v_mfma_f32_16x16x32_bf16 v[84:87], v[188:191], v[108:111], v[84:87]
	v_mfma_f32_16x16x32_bf16 v[80:83], v[188:191], v[220:223], v[80:83]
	v_mfma_f32_16x16x32_bf16 v[76:79], v[192:195], v[104:107], v[76:79]
	v_mfma_f32_16x16x32_bf16 v[72:75], v[192:195], v[216:219], v[72:75]
	v_mfma_f32_16x16x32_bf16 v[68:71], v[204:207], v[108:111], v[68:71]
	v_mfma_f32_16x16x32_bf16 v[64:67], v[204:207], v[220:223], v[64:67]
	v_mfma_f32_16x16x32_bf16 v[224:227], v[180:183], v[108:111], v[92:95]
	v_mfma_f32_16x16x32_bf16 v[174:177], v[180:183], v[220:223], v[88:91]
	v_mfma_f32_16x16x32_bf16 v[178:181], v[196:199], v[108:111], v[76:79]
	v_mfma_f32_16x16x32_bf16 v[182:185], v[196:199], v[220:223], v[72:75]
	s_setprio 0
	s_barrier
	s_nop 0
	ds_read_b128 v[72:75], v159 offset:16384
	ds_read_b128 v[76:79], v159 offset:17408
	ds_read_b128 v[88:91], v158 offset:16384
	ds_read_b128 v[92:95], v158 offset:17408
	ds_read_b128 v[186:189], v157 offset:16384
	ds_read_b128 v[190:193], v157 offset:17408
	ds_read_b128 v[194:197], v156 offset:16384
	ds_read_b128 v[198:201], v156 offset:17408
	s_waitcnt vmcnt(4)
	s_barrier
	s_waitcnt lgkmcnt(0)
	s_setprio 1
	s_waitcnt lgkmcnt(0)
	v_mfma_f32_16x16x32_bf16 v[60:63], v[72:75], v[132:135], v[60:63]
	v_mfma_f32_16x16x32_bf16 v[56:59], v[72:75], v[140:143], v[56:59]
	v_mfma_f32_16x16x32_bf16 v[52:55], v[88:91], v[132:135], v[52:55]
	v_mfma_f32_16x16x32_bf16 v[48:51], v[88:91], v[140:143], v[48:51]
	v_mfma_f32_16x16x32_bf16 v[36:39], v[194:197], v[132:135], v[36:39]
	v_mfma_f32_16x16x32_bf16 v[32:35], v[194:197], v[140:143], v[32:35]
	v_mfma_f32_16x16x32_bf16 v[60:63], v[76:79], v[136:139], v[60:63]
	v_mfma_f32_16x16x32_bf16 v[56:59], v[76:79], v[144:147], v[56:59]
	v_mfma_f32_16x16x32_bf16 v[52:55], v[92:95], v[136:139], v[52:55]
	v_mfma_f32_16x16x32_bf16 v[48:51], v[92:95], v[144:147], v[48:51]
	v_mfma_f32_16x16x32_bf16 v[44:47], v[186:189], v[132:135], v[44:47]
	v_mfma_f32_16x16x32_bf16 v[40:43], v[186:189], v[140:143], v[40:43]
	v_mfma_f32_16x16x32_bf16 v[36:39], v[198:201], v[136:139], v[36:39]
	v_mfma_f32_16x16x32_bf16 v[32:35], v[198:201], v[144:147], v[32:35]
	v_mfma_f32_16x16x32_bf16 v[202:205], v[190:193], v[136:139], v[44:47]
	v_mfma_f32_16x16x32_bf16 v[228:231], v[190:193], v[144:147], v[40:43]
	s_setprio 0
	s_setprio 1
	v_mfma_f32_16x16x32_bf16 v[20:23], v[88:91], v[104:107], v[20:23]
	v_mfma_f32_16x16x32_bf16 v[16:19], v[88:91], v[216:219], v[16:19]
	v_mfma_f32_16x16x32_bf16 v[4:7], v[194:197], v[104:107], v[4:7]
	v_mfma_f32_16x16x32_bf16 v[0:3], v[194:197], v[216:219], v[0:3]
	v_mfma_f32_16x16x32_bf16 v[28:31], v[72:75], v[104:107], v[28:31]
	v_mfma_f32_16x16x32_bf16 v[24:27], v[72:75], v[216:219], v[24:27]
	v_mfma_f32_16x16x32_bf16 v[20:23], v[92:95], v[108:111], v[20:23]
	v_mfma_f32_16x16x32_bf16 v[16:19], v[92:95], v[220:223], v[16:19]
	v_mfma_f32_16x16x32_bf16 v[12:15], v[186:189], v[104:107], v[12:15]
	v_mfma_f32_16x16x32_bf16 v[8:11], v[186:189], v[216:219], v[8:11]
	v_mfma_f32_16x16x32_bf16 v[4:7], v[198:201], v[108:111], v[4:7]
	v_mfma_f32_16x16x32_bf16 v[0:3], v[198:201], v[220:223], v[0:3]
	v_mfma_f32_16x16x32_bf16 v[132:135], v[76:79], v[108:111], v[28:31]
	v_mfma_f32_16x16x32_bf16 v[136:139], v[76:79], v[220:223], v[24:27]
	v_mfma_f32_16x16x32_bf16 v[140:143], v[190:193], v[108:111], v[12:15]
	v_mfma_f32_16x16x32_bf16 v[144:147], v[190:193], v[220:223], v[8:11]
	s_setprio 0
	s_barrier
	s_nop 0
	ds_read_b128 v[8:11], v162
	ds_read_b128 v[12:15], v162 offset:1024
	ds_read_b128 v[186:189], v162 offset:2048
	ds_read_b128 v[190:193], v162 offset:3072
	ds_read_b128 v[24:27], v159 offset:32768
	ds_read_b128 v[28:31], v159 offset:33792
	ds_read_b128 v[40:43], v158 offset:32768
	ds_read_b128 v[44:47], v158 offset:33792
	ds_read_b128 v[194:197], v157 offset:32768
	ds_read_b128 v[198:201], v157 offset:33792
	ds_read_b128 v[216:219], v156 offset:32768
	ds_read_b128 v[220:223], v156 offset:33792
	s_waitcnt vmcnt(2)
	s_barrier
; #define LDA(dst, b, h) for (int m = 0; m < 4; ++m) for (int k = 0; k < 2; ++k) \
;     dst[m][k] = *reinterpret_cast<const bf16x8*>((char*)SA(b, h) + lds_byte(wr * 64 + m * 16 + fr, k * 32 + fq * 8))
; #define LDB(dst, b, h) for (int n = 0; n < 2; ++n) for (int k = 0; k < 2; ++k) \
;     dst[n][k] = *reinterpret_cast<const bf16x8*>((char*)SB(b, h) + lds_byte(wc * 32 + n * 16 + fr, k * 32 + fq * 8))
; #define MMA(ai, bj, At, Bq) do { __builtin_amdgcn_s_setprio(1); \
;     for (int m = 0; m < 4; ++m) for (int n = 0; n < 2; ++n) for (int k = 0; k < 2; ++k) \
;       acc[ai][bj][m][n] = __builtin_amdgcn_mfma_f32_16x16x32_bf16(At[m][k], Bq[n][k], acc[ai][bj][m][n], 0, 0, 0); \
;     __builtin_amdgcn_s_setprio(0); } while (0)
; #define WAIT_V(n) asm volatile("s_waitcnt vmcnt(" #n ")" ::: "memory")
; #define WAIT_L(n) asm volatile("s_waitcnt lgkmcnt(" #n ")" ::: "memory")
; #define BAR __builtin_amdgcn_s_barrier()
; template <class Epi>
; __device__ __forceinline__ void gemm_tile(const u16* __restrict__ A, const u16* __restrict__ Bt, int K,
;                                           int brow, int bcol, bool first, bool has_next, int nbrow, int nbcol, Epi epi) {
;     ...
;   { LDB(B0, 1, 0); LDA(At, 1, 0); WAIT_V(2); BAR; WAIT_L(0); MMA(0, 0, At, B0); BAR;
;     LDB(B1, 1, 1); WAIT_V(0); BAR; WAIT_L(0); MMA(0, 1, At, B1); BAR;
;     LDA(At, 1, 1); BAR; WAIT_L(0); MMA(1, 0, At, B0); MMA(1, 1, At, B1); BAR; }
;   if (wr == 0) BAR;
	s_waitcnt lgkmcnt(0)
	s_setprio 1
	s_waitcnt lgkmcnt(0)
	v_mfma_f32_16x16x32_bf16 v[72:75], v[24:27], v[8:11], v[124:127]
	v_mfma_f32_16x16x32_bf16 v[124:127], v[28:31], v[12:15], v[72:75]
	v_mfma_f32_16x16x32_bf16 v[72:75], v[24:27], v[186:189], v[120:123]
	v_mfma_f32_16x16x32_bf16 v[120:123], v[28:31], v[190:193], v[72:75]
	v_mfma_f32_16x16x32_bf16 v[72:75], v[40:43], v[8:11], v[116:119]
	v_mfma_f32_16x16x32_bf16 v[108:111], v[44:47], v[12:15], v[72:75]
	v_mfma_f32_16x16x32_bf16 v[72:75], v[40:43], v[186:189], v[112:115]
	v_mfma_f32_16x16x32_bf16 v[104:107], v[44:47], v[190:193], v[72:75]
	v_mfma_f32_16x16x32_bf16 v[72:75], v[194:197], v[8:11], v[208:211]
	v_mfma_f32_16x16x32_bf16 v[92:95], v[198:201], v[12:15], v[72:75]
	v_mfma_f32_16x16x32_bf16 v[72:75], v[194:197], v[186:189], v[212:215]
	v_mfma_f32_16x16x32_bf16 v[88:91], v[198:201], v[190:193], v[72:75]
	v_mfma_f32_16x16x32_bf16 v[72:75], v[216:219], v[8:11], v[100:103]
	v_mfma_f32_16x16x32_bf16 v[76:79], v[220:223], v[12:15], v[72:75]
	v_mfma_f32_16x16x32_bf16 v[72:75], v[216:219], v[186:189], v[96:99]
	v_mfma_f32_16x16x32_bf16 v[72:75], v[220:223], v[190:193], v[72:75]
	s_setprio 0
	s_barrier
	ds_read_b128 v[206:209], v161
	ds_read_b128 v[210:213], v161 offset:1024
	ds_read_b128 v[232:235], v161 offset:2048
	ds_read_b128 v[236:239], v161 offset:3072
	s_waitcnt vmcnt(0)
	s_barrier
	s_waitcnt lgkmcnt(0)
	s_setprio 1
	s_waitcnt lgkmcnt(0)
	v_mfma_f32_16x16x32_bf16 v[96:99], v[24:27], v[206:209], v[224:227]
	v_mfma_f32_16x16x32_bf16 v[24:27], v[24:27], v[232:235], v[174:177]
	v_mfma_f32_16x16x32_bf16 v[112:115], v[28:31], v[236:239], v[24:27]
	v_mfma_f32_16x16x32_bf16 v[24:27], v[40:43], v[206:209], v[84:87]
	v_mfma_f32_16x16x32_bf16 v[100:103], v[44:47], v[210:213], v[24:27]
	v_mfma_f32_16x16x32_bf16 v[24:27], v[40:43], v[232:235], v[80:83]
	v_mfma_f32_16x16x32_bf16 v[116:119], v[28:31], v[210:213], v[96:99]
	v_mfma_f32_16x16x32_bf16 v[96:99], v[44:47], v[236:239], v[24:27]
	v_mfma_f32_16x16x32_bf16 v[24:27], v[194:197], v[206:209], v[178:181]
	v_mfma_f32_16x16x32_bf16 v[84:87], v[198:201], v[210:213], v[24:27]
	v_mfma_f32_16x16x32_bf16 v[24:27], v[194:197], v[232:235], v[182:185]
	v_mfma_f32_16x16x32_bf16 v[80:83], v[198:201], v[236:239], v[24:27]
	v_mfma_f32_16x16x32_bf16 v[24:27], v[216:219], v[206:209], v[68:71]
	v_mfma_f32_16x16x32_bf16 v[68:71], v[220:223], v[210:213], v[24:27]
	v_mfma_f32_16x16x32_bf16 v[24:27], v[216:219], v[232:235], v[64:67]
	v_mfma_f32_16x16x32_bf16 v[64:67], v[220:223], v[236:239], v[24:27]
	s_setprio 0
	s_barrier
	ds_read_b128 v[174:177], v159 offset:49152
	ds_read_b128 v[178:181], v159 offset:50176
	ds_read_b128 v[182:185], v158 offset:49152
	ds_read_b128 v[194:197], v158 offset:50176
	ds_read_b128 v[198:201], v157 offset:49152
	ds_read_b128 v[214:217], v157 offset:50176
	ds_read_b128 v[218:221], v156 offset:49152
	ds_read_b128 v[156:159], v156 offset:50176
	s_barrier
	s_waitcnt lgkmcnt(0)
	s_setprio 1
	s_waitcnt lgkmcnt(0)
	v_mfma_f32_16x16x32_bf16 v[24:27], v[174:177], v[8:11], v[60:63]
	v_mfma_f32_16x16x32_bf16 v[60:63], v[178:181], v[12:15], v[24:27]
	v_mfma_f32_16x16x32_bf16 v[24:27], v[174:177], v[186:189], v[56:59]
	v_mfma_f32_16x16x32_bf16 v[56:59], v[178:181], v[190:193], v[24:27]
	v_mfma_f32_16x16x32_bf16 v[24:27], v[182:185], v[8:11], v[52:55]
	v_mfma_f32_16x16x32_bf16 v[44:47], v[194:197], v[12:15], v[24:27]
	v_mfma_f32_16x16x32_bf16 v[24:27], v[182:185], v[186:189], v[48:51]
	v_mfma_f32_16x16x32_bf16 v[40:43], v[194:197], v[190:193], v[24:27]
	v_mfma_f32_16x16x32_bf16 v[24:27], v[198:201], v[8:11], v[202:205]
	v_mfma_f32_16x16x32_bf16 v[8:11], v[218:221], v[8:11], v[36:39]
	v_mfma_f32_16x16x32_bf16 v[28:31], v[214:217], v[12:15], v[24:27]
	v_mfma_f32_16x16x32_bf16 v[24:27], v[198:201], v[186:189], v[228:231]
	v_mfma_f32_16x16x32_bf16 v[12:15], v[156:159], v[12:15], v[8:11]
	v_mfma_f32_16x16x32_bf16 v[8:11], v[218:221], v[186:189], v[32:35]
	v_mfma_f32_16x16x32_bf16 v[24:27], v[214:217], v[190:193], v[24:27]
	v_mfma_f32_16x16x32_bf16 v[8:11], v[156:159], v[190:193], v[8:11]
	s_setprio 0
	s_setprio 1
	v_mfma_f32_16x16x32_bf16 v[32:35], v[174:177], v[206:209], v[132:135]
	v_mfma_f32_16x16x32_bf16 v[52:55], v[178:181], v[210:213], v[32:35]
	v_mfma_f32_16x16x32_bf16 v[32:35], v[174:177], v[232:235], v[136:139]
	v_mfma_f32_16x16x32_bf16 v[16:19], v[182:185], v[232:235], v[16:19]
	v_mfma_f32_16x16x32_bf16 v[48:51], v[178:181], v[236:239], v[32:35]
	v_mfma_f32_16x16x32_bf16 v[20:23], v[182:185], v[206:209], v[20:23]
	v_mfma_f32_16x16x32_bf16 v[32:35], v[194:197], v[236:239], v[16:19]
	v_mfma_f32_16x16x32_bf16 v[16:19], v[198:201], v[206:209], v[140:143]
	v_mfma_f32_16x16x32_bf16 v[36:39], v[194:197], v[210:213], v[20:23]
	v_mfma_f32_16x16x32_bf16 v[20:23], v[214:217], v[210:213], v[16:19]
	v_mfma_f32_16x16x32_bf16 v[16:19], v[198:201], v[232:235], v[144:147]
	v_mfma_f32_16x16x32_bf16 v[4:7], v[218:221], v[206:209], v[4:7]
	v_mfma_f32_16x16x32_bf16 v[0:3], v[218:221], v[232:235], v[0:3]
	v_mfma_f32_16x16x32_bf16 v[16:19], v[214:217], v[236:239], v[16:19]
	v_mfma_f32_16x16x32_bf16 v[4:7], v[156:159], v[210:213], v[4:7]
	v_mfma_f32_16x16x32_bf16 v[0:3], v[156:159], v[236:239], v[0:3]
	s_setprio 0
	v_cmp_gt_u32_e32 vcc, s62, v148
	s_barrier
	s_and_saveexec_b64 s[26:27], vcc
	s_cbranch_execz .LBB0_460
	s_barrier

; #define LDA(dst, b, h) for (int m = 0; m < 4; ++m) for (int k = 0; k < 2; ++k) \
;     dst[m][k] = *reinterpret_cast<const bf16x8*>((char*)SA(b, h) + lds_byte(wr * 64 + m * 16 + fr, k * 32 + fq * 8))
; #define LDB(dst, b, h) for (int n = 0; n < 2; ++n) for (int k = 0; k < 2; ++k) \
;     dst[n][k] = *reinterpret_cast<const bf16x8*>((char*)SB(b, h) + lds_byte(wc * 32 + n * 16 + fr, k * 32 + fq * 8))
; #define MMA(ai, bj, At, Bq) do { __builtin_amdgcn_s_setprio(1); \
;     for (int m = 0; m < 4; ++m) for (int n = 0; n < 2; ++n) for (int k = 0; k < 2; ++k) \
;       acc[ai][bj][m][n] = __builtin_amdgcn_mfma_f32_16x16x32_bf16(At[m][k], Bq[n][k], acc[ai][bj][m][n], 0, 0, 0); \
;     __builtin_amdgcn_s_setprio(0); } while (0)
; #define WAIT_L(n) asm volatile("s_waitcnt lgkmcnt(" #n ")" ::: "memory")
; #define BAR __builtin_amdgcn_s_barrier()
; #define SCHED __builtin_amdgcn_sched_barrier(0)
; template <class Epi>
; __device__ __forceinline__ void gemm_tile(const u16* __restrict__ A, const u16* __restrict__ Bt, int K,
;                                           int brow, int bcol, bool first, bool has_next, int nbrow, int nbcol, Epi epi) {
;     ...
;     LDB(B0, 0, 0); SCHED; LDA(At, 0, 0); STAGE(SA(1, 1), A, brow + HALF, t + 1);
;     WAIT_L(8); BAR; WAIT_L(0); MMA(0, 0, At, B0); BAR; SCHED;
;     LDB(B1, 0, 1); STAGE(SB(0, 0), Bt, bcol, t + 2);
;     BAR; WAIT_L(0); MMA(0, 1, At, B1); BAR;
;     LDA(At, 0, 1); STAGE(SA(0, 0), A, brow, t + 2);
;     BAR; WAIT_L(0); MMA(1, 0, At, B0); BAR; SCHED;
.LBB0_592:
	ds_read_b128 v[166:169], v164
	ds_read_b128 v[176:179], v164 offset:1024
	ds_read_b128 v[180:183], v164 offset:2048
	ds_read_b128 v[184:187], v164 offset:3072
	v_add_u32_e32 v173, 0xc000, v153
	v_lshl_add_u64 v[170:171], s[40:41], 0, v[144:145]
	v_readfirstlane_b32 s3, v173
	v_lshl_add_u64 v[174:175], v[170:171], 0, s[12:13]
	s_mov_b32 m0, s3
	ds_read_b128 v[188:191], v159
	ds_read_b128 v[192:195], v159 offset:1024
	ds_read_b128 v[196:199], v158
	ds_read_b128 v[200:203], v158 offset:1024
	ds_read_b128 v[204:207], v157
	ds_read_b128 v[208:211], v157 offset:1024
	ds_read_b128 v[212:215], v156
	ds_read_b128 v[216:219], v156 offset:1024
	global_load_lds_dwordx4 v[174:175], off
	v_add_u32_e32 v174, 0xe000, v153
	v_lshl_add_u64 v[236:237], s[40:41], 0, v[146:147]
	v_readfirstlane_b32 s3, v174
	v_lshl_add_u64 v[220:221], v[236:237], 0, s[12:13]
	s_mov_b32 m0, s3
	s_nop 0
	global_load_lds_dwordx4 v[220:221], off
	s_waitcnt lgkmcnt(8)
	s_barrier
	s_waitcnt lgkmcnt(0)
	s_setprio 1
	s_waitcnt lgkmcnt(0)
	v_mfma_f32_16x16x32_bf16 v[124:127], v[188:191], v[166:169], v[124:127]
	v_mfma_f32_16x16x32_bf16 v[120:123], v[188:191], v[180:183], v[120:123]
	v_mfma_f32_16x16x32_bf16 v[116:119], v[196:199], v[166:169], v[116:119]
	v_mfma_f32_16x16x32_bf16 v[112:115], v[196:199], v[180:183], v[112:115]
	v_mfma_f32_16x16x32_bf16 v[108:111], v[204:207], v[166:169], v[108:111]
	v_mfma_f32_16x16x32_bf16 v[104:107], v[204:207], v[180:183], v[104:107]
	v_mfma_f32_16x16x32_bf16 v[100:103], v[212:215], v[166:169], v[100:103]
	v_mfma_f32_16x16x32_bf16 v[96:99], v[212:215], v[180:183], v[96:99]
	v_mfma_f32_16x16x32_bf16 v[124:127], v[192:195], v[176:179], v[124:127]
	v_mfma_f32_16x16x32_bf16 v[120:123], v[192:195], v[184:187], v[120:123]
	v_mfma_f32_16x16x32_bf16 v[116:119], v[200:203], v[176:179], v[116:119]
	v_mfma_f32_16x16x32_bf16 v[112:115], v[200:203], v[184:187], v[112:115]
	v_mfma_f32_16x16x32_bf16 v[108:111], v[208:211], v[176:179], v[108:111]
	v_mfma_f32_16x16x32_bf16 v[104:107], v[208:211], v[184:187], v[104:107]
	v_mfma_f32_16x16x32_bf16 v[100:103], v[216:219], v[176:179], v[100:103]
	v_mfma_f32_16x16x32_bf16 v[96:99], v[216:219], v[184:187], v[96:99]
	s_setprio 0
	s_barrier
	v_lshl_add_u64 v[240:241], s[40:41], 0, v[132:133]
	v_readfirstlane_b32 s3, v154
	v_add_u32_e32 v165, 0x2000, v154
	v_lshl_add_u64 v[238:239], v[240:241], 0, s[14:15]
	s_mov_b32 m0, s3
	v_lshl_add_u64 v[242:243], s[40:41], 0, v[134:135]
	v_readfirstlane_b32 s3, v165
	ds_read_b128 v[220:223], v163
	ds_read_b128 v[224:227], v163 offset:1024
	ds_read_b128 v[228:231], v163 offset:2048
	ds_read_b128 v[232:235], v163 offset:3072
	global_load_lds_dwordx4 v[238:239], off
	v_lshl_add_u64 v[238:239], v[242:243], 0, s[14:15]
	s_mov_b32 m0, s3
	s_nop 0
	global_load_lds_dwordx4 v[238:239], off
	s_barrier
	s_waitcnt lgkmcnt(0)
	s_setprio 1
	s_waitcnt lgkmcnt(0)
	s_nop 0
	v_mfma_f32_16x16x32_bf16 v[92:95], v[188:191], v[220:223], v[92:95]
	v_mfma_f32_16x16x32_bf16 v[88:91], v[188:191], v[228:231], v[88:91]
	v_mfma_f32_16x16x32_bf16 v[84:87], v[196:199], v[220:223], v[84:87]
	v_mfma_f32_16x16x32_bf16 v[80:83], v[196:199], v[228:231], v[80:83]
	v_mfma_f32_16x16x32_bf16 v[76:79], v[204:207], v[220:223], v[76:79]
	v_mfma_f32_16x16x32_bf16 v[72:75], v[204:207], v[228:231], v[72:75]
	v_mfma_f32_16x16x32_bf16 v[68:71], v[212:215], v[220:223], v[68:71]
	v_mfma_f32_16x16x32_bf16 v[64:67], v[212:215], v[228:231], v[64:67]
	v_mfma_f32_16x16x32_bf16 v[92:95], v[192:195], v[224:227], v[92:95]
	v_mfma_f32_16x16x32_bf16 v[88:91], v[192:195], v[232:235], v[88:91]
	v_mfma_f32_16x16x32_bf16 v[84:87], v[200:203], v[224:227], v[84:87]
	v_mfma_f32_16x16x32_bf16 v[80:83], v[200:203], v[232:235], v[80:83]
	v_mfma_f32_16x16x32_bf16 v[76:79], v[208:211], v[224:227], v[76:79]
	v_mfma_f32_16x16x32_bf16 v[72:75], v[208:211], v[232:235], v[72:75]
	v_mfma_f32_16x16x32_bf16 v[68:71], v[216:219], v[224:227], v[68:71]
	v_mfma_f32_16x16x32_bf16 v[64:67], v[216:219], v[232:235], v[64:67]
	s_setprio 0
	v_lshl_add_u64 v[244:245], s[40:41], 0, v[136:137]
	v_readfirstlane_b32 s3, v153
	v_lshl_add_u64 v[238:239], v[244:245], 0, s[16:17]
	s_mov_b32 m0, s3
	v_lshl_add_u64 v[246:247], s[40:41], 0, v[138:139]
	v_readfirstlane_b32 s3, v152
	s_barrier
	ds_read_b128 v[188:191], v159 offset:16384
	ds_read_b128 v[192:195], v159 offset:17408
	ds_read_b128 v[196:199], v158 offset:16384
	ds_read_b128 v[200:203], v158 offset:17408
	ds_read_b128 v[204:207], v157 offset:16384
	ds_read_b128 v[208:211], v157 offset:17408
	ds_read_b128 v[212:215], v156 offset:16384
	ds_read_b128 v[216:219], v156 offset:17408
	global_load_lds_dwordx4 v[238:239], off
	v_lshl_add_u64 v[238:239], v[246:247], 0, s[16:17]
	s_mov_b32 m0, s3
	s_nop 0
	global_load_lds_dwordx4 v[238:239], off
	s_barrier
	s_waitcnt lgkmcnt(0)
	s_setprio 1
	s_waitcnt lgkmcnt(0)
	s_nop 0
	v_mfma_f32_16x16x32_bf16 v[60:63], v[188:191], v[166:169], v[60:63]
	v_mfma_f32_16x16x32_bf16 v[56:59], v[188:191], v[180:183], v[56:59]
	v_mfma_f32_16x16x32_bf16 v[52:55], v[196:199], v[166:169], v[52:55]
	v_mfma_f32_16x16x32_bf16 v[48:51], v[196:199], v[180:183], v[48:51]
	v_mfma_f32_16x16x32_bf16 v[44:47], v[204:207], v[166:169], v[44:47]
	v_mfma_f32_16x16x32_bf16 v[40:43], v[204:207], v[180:183], v[40:43]
	v_mfma_f32_16x16x32_bf16 v[36:39], v[212:215], v[166:169], v[36:39]
	v_mfma_f32_16x16x32_bf16 v[32:35], v[212:215], v[180:183], v[32:35]
	v_mfma_f32_16x16x32_bf16 v[60:63], v[192:195], v[176:179], v[60:63]
	v_mfma_f32_16x16x32_bf16 v[56:59], v[192:195], v[184:187], v[56:59]
	v_mfma_f32_16x16x32_bf16 v[52:55], v[200:203], v[176:179], v[52:55]
	v_mfma_f32_16x16x32_bf16 v[48:51], v[200:203], v[184:187], v[48:51]
	v_mfma_f32_16x16x32_bf16 v[44:47], v[208:211], v[176:179], v[44:47]
	v_mfma_f32_16x16x32_bf16 v[40:43], v[208:211], v[184:187], v[40:43]
	v_mfma_f32_16x16x32_bf16 v[36:39], v[216:219], v[176:179], v[36:39]
	v_mfma_f32_16x16x32_bf16 v[32:35], v[216:219], v[184:187], v[32:35]
	s_setprio 0
	s_barrier
; #define LDA(dst, b, h) for (int m = 0; m < 4; ++m) for (int k = 0; k < 2; ++k) \
;     dst[m][k] = *reinterpret_cast<const bf16x8*>((char*)SA(b, h) + lds_byte(wr * 64 + m * 16 + fr, k * 32 + fq * 8))
; #define LDB(dst, b, h) for (int n = 0; n < 2; ++n) for (int k = 0; k < 2; ++k) \
;     dst[n][k] = *reinterpret_cast<const bf16x8*>((char*)SB(b, h) + lds_byte(wc * 32 + n * 16 + fr, k * 32 + fq * 8))
; #define MMA(ai, bj, At, Bq) do { __builtin_amdgcn_s_setprio(1); \
;     for (int m = 0; m < 4; ++m) for (int n = 0; n < 2; ++n) for (int k = 0; k < 2; ++k) \
;       acc[ai][bj][m][n] = __builtin_amdgcn_mfma_f32_16x16x32_bf16(At[m][k], Bq[n][k], acc[ai][bj][m][n], 0, 0, 0); \
;     __builtin_amdgcn_s_setprio(0); } while (0)
; #define WAIT_V(n) asm volatile("s_waitcnt vmcnt(" #n ")" ::: "memory")
; #define WAIT_L(n) asm volatile("s_waitcnt lgkmcnt(" #n ")" ::: "memory")
; #define BAR __builtin_amdgcn_s_barrier()
; #define SCHED __builtin_amdgcn_sched_barrier(0)
; template <class Epi>
; __device__ __forceinline__ void gemm_tile(const u16* __restrict__ A, const u16* __restrict__ Bt, int K,
;                                           int brow, int bcol, bool first, bool has_next, int nbrow, int nbcol, Epi epi) {
;     ...
;     STAGE(SB(0, 1), Bt, bcol + HALF, t + 2);
;     WAIT_V(6); BAR; MMA(1, 1, At, B1); BAR;
;     LDB(B0, 1, 0); SCHED; LDA(At, 1, 0); STAGE(SA(0, 1), A, brow + HALF, t + 2);
;     WAIT_L(8); BAR; WAIT_L(0); MMA(0, 0, At, B0); BAR; SCHED;
;     LDB(B1, 1, 1); STAGE(SB(1, 0), Bt, bcol, t + 3);
;     BAR; WAIT_L(0); MMA(0, 1, At, B1); BAR;
;     LDA(At, 1, 1); STAGE(SA(1, 0), A, brow, t + 3);
	v_lshl_add_u64 v[248:249], s[40:41], 0, v[140:141]
	v_readfirstlane_b32 s3, v151
	v_lshl_add_u64 v[166:167], v[248:249], 0, s[14:15]
	s_mov_b32 m0, s3
	v_lshl_add_u64 v[250:251], s[40:41], 0, v[142:143]
	global_load_lds_dwordx4 v[166:167], off
	v_add_u32_e32 v166, 0x2000, v151
	v_lshl_add_u64 v[168:169], v[250:251], 0, s[14:15]
	v_readfirstlane_b32 s3, v166
	s_mov_b32 m0, s3
	s_nop 0
	global_load_lds_dwordx4 v[168:169], off
	s_waitcnt vmcnt(6)
	s_barrier
	s_setprio 1
	v_mfma_f32_16x16x32_bf16 v[28:31], v[188:191], v[220:223], v[28:31]
	v_mfma_f32_16x16x32_bf16 v[24:27], v[188:191], v[228:231], v[24:27]
	v_mfma_f32_16x16x32_bf16 v[20:23], v[196:199], v[220:223], v[20:23]
	v_mfma_f32_16x16x32_bf16 v[16:19], v[196:199], v[228:231], v[16:19]
	v_mfma_f32_16x16x32_bf16 v[12:15], v[204:207], v[220:223], v[12:15]
	v_mfma_f32_16x16x32_bf16 v[8:11], v[204:207], v[228:231], v[8:11]
	v_mfma_f32_16x16x32_bf16 v[4:7], v[212:215], v[220:223], v[4:7]
	v_mfma_f32_16x16x32_bf16 v[0:3], v[212:215], v[228:231], v[0:3]
	v_mfma_f32_16x16x32_bf16 v[28:31], v[192:195], v[224:227], v[28:31]
	v_mfma_f32_16x16x32_bf16 v[24:27], v[192:195], v[232:235], v[24:27]
	v_mfma_f32_16x16x32_bf16 v[20:23], v[200:203], v[224:227], v[20:23]
	v_mfma_f32_16x16x32_bf16 v[16:19], v[200:203], v[232:235], v[16:19]
	v_mfma_f32_16x16x32_bf16 v[12:15], v[208:211], v[224:227], v[12:15]
	v_mfma_f32_16x16x32_bf16 v[8:11], v[208:211], v[232:235], v[8:11]
	v_mfma_f32_16x16x32_bf16 v[4:7], v[216:219], v[224:227], v[4:7]
	v_mfma_f32_16x16x32_bf16 v[0:3], v[216:219], v[232:235], v[0:3]
	s_setprio 0
	s_barrier
	ds_read_b128 v[176:179], v161
	ds_read_b128 v[180:183], v161 offset:1024
	ds_read_b128 v[184:187], v161 offset:2048
	ds_read_b128 v[188:191], v161 offset:3072
	v_readfirstlane_b32 s3, v150
	v_lshl_add_u64 v[168:169], v[170:171], 0, s[16:17]
	s_mov_b32 m0, s3
	v_readfirstlane_b32 s3, v149
	ds_read_b128 v[192:195], v159 offset:32768
	ds_read_b128 v[196:199], v159 offset:33792
	ds_read_b128 v[200:203], v158 offset:32768
	ds_read_b128 v[204:207], v158 offset:33792
	ds_read_b128 v[208:211], v157 offset:32768
	ds_read_b128 v[212:215], v157 offset:33792
	ds_read_b128 v[216:219], v156 offset:32768
	ds_read_b128 v[220:223], v156 offset:33792
	global_load_lds_dwordx4 v[168:169], off
	v_lshl_add_u64 v[168:169], v[236:237], 0, s[16:17]
	s_mov_b32 m0, s3
	s_nop 0
	global_load_lds_dwordx4 v[168:169], off
	s_waitcnt lgkmcnt(8)
	s_barrier
	s_waitcnt lgkmcnt(0)
	s_setprio 1
	s_waitcnt lgkmcnt(0)
	v_mfma_f32_16x16x32_bf16 v[124:127], v[192:195], v[176:179], v[124:127]
	v_mfma_f32_16x16x32_bf16 v[120:123], v[192:195], v[184:187], v[120:123]
	v_mfma_f32_16x16x32_bf16 v[116:119], v[200:203], v[176:179], v[116:119]
	v_mfma_f32_16x16x32_bf16 v[112:115], v[200:203], v[184:187], v[112:115]
	v_mfma_f32_16x16x32_bf16 v[108:111], v[208:211], v[176:179], v[108:111]
	v_mfma_f32_16x16x32_bf16 v[104:107], v[208:211], v[184:187], v[104:107]
	v_mfma_f32_16x16x32_bf16 v[100:103], v[216:219], v[176:179], v[100:103]
	v_mfma_f32_16x16x32_bf16 v[96:99], v[216:219], v[184:187], v[96:99]
	v_mfma_f32_16x16x32_bf16 v[124:127], v[196:199], v[180:183], v[124:127]
	v_mfma_f32_16x16x32_bf16 v[120:123], v[196:199], v[188:191], v[120:123]
	v_mfma_f32_16x16x32_bf16 v[116:119], v[204:207], v[180:183], v[116:119]
	v_mfma_f32_16x16x32_bf16 v[112:115], v[204:207], v[188:191], v[112:115]
	v_mfma_f32_16x16x32_bf16 v[108:111], v[212:215], v[180:183], v[108:111]
	v_mfma_f32_16x16x32_bf16 v[104:107], v[212:215], v[188:191], v[104:107]
	v_mfma_f32_16x16x32_bf16 v[100:103], v[220:223], v[180:183], v[100:103]
	v_mfma_f32_16x16x32_bf16 v[96:99], v[220:223], v[188:191], v[96:99]
	s_setprio 0
	s_barrier
	v_add_u32_e32 v167, s84, v155
	v_lshl_add_u64 v[168:169], v[240:241], 0, s[18:19]
	v_readfirstlane_b32 s3, v167
	s_mov_b32 m0, s3
	ds_read_b128 v[224:227], v160
	ds_read_b128 v[228:231], v160 offset:1024
	ds_read_b128 v[232:235], v160 offset:2048
	ds_read_b128 v[236:239], v160 offset:3072
	global_load_lds_dwordx4 v[168:169], off
	v_add_u32_e32 v168, 0x2000, v167
	v_lshl_add_u64 v[170:171], v[242:243], 0, s[18:19]
	v_readfirstlane_b32 s3, v168
	s_mov_b32 m0, s3
	s_nop 0
	global_load_lds_dwordx4 v[170:171], off
	s_barrier
	s_waitcnt lgkmcnt(0)
	s_setprio 1
	s_waitcnt lgkmcnt(0)
	v_mfma_f32_16x16x32_bf16 v[92:95], v[192:195], v[224:227], v[92:95]
	v_mfma_f32_16x16x32_bf16 v[88:91], v[192:195], v[232:235], v[88:91]
	v_mfma_f32_16x16x32_bf16 v[84:87], v[200:203], v[224:227], v[84:87]
	v_mfma_f32_16x16x32_bf16 v[80:83], v[200:203], v[232:235], v[80:83]
	v_mfma_f32_16x16x32_bf16 v[76:79], v[208:211], v[224:227], v[76:79]
	v_mfma_f32_16x16x32_bf16 v[72:75], v[208:211], v[232:235], v[72:75]
	v_mfma_f32_16x16x32_bf16 v[68:71], v[216:219], v[224:227], v[68:71]
	v_mfma_f32_16x16x32_bf16 v[64:67], v[216:219], v[232:235], v[64:67]
	v_mfma_f32_16x16x32_bf16 v[92:95], v[196:199], v[228:231], v[92:95]
	v_mfma_f32_16x16x32_bf16 v[88:91], v[196:199], v[236:239], v[88:91]
	v_mfma_f32_16x16x32_bf16 v[84:87], v[204:207], v[228:231], v[84:87]
	v_mfma_f32_16x16x32_bf16 v[80:83], v[204:207], v[236:239], v[80:83]
	v_mfma_f32_16x16x32_bf16 v[76:79], v[212:215], v[228:231], v[76:79]
	v_mfma_f32_16x16x32_bf16 v[72:75], v[212:215], v[236:239], v[72:75]
	v_mfma_f32_16x16x32_bf16 v[68:71], v[220:223], v[228:231], v[68:71]
	v_mfma_f32_16x16x32_bf16 v[64:67], v[220:223], v[236:239], v[64:67]
	s_setprio 0
	v_add_u32_e32 v169, 0x8000, v153
	v_lshl_add_u64 v[170:171], v[244:245], 0, s[20:21]
	v_readfirstlane_b32 s3, v169
	s_mov_b32 m0, s3
	s_barrier
; #define LDA(dst, b, h) for (int m = 0; m < 4; ++m) for (int k = 0; k < 2; ++k) \
;     dst[m][k] = *reinterpret_cast<const bf16x8*>((char*)SA(b, h) + lds_byte(wr * 64 + m * 16 + fr, k * 32 + fq * 8))
; #define LDB(dst, b, h) for (int n = 0; n < 2; ++n) for (int k = 0; k < 2; ++k) \
;     dst[n][k] = *reinterpret_cast<const bf16x8*>((char*)SB(b, h) + lds_byte(wc * 32 + n * 16 + fr, k * 32 + fq * 8))
; #define MMA(ai, bj, At, Bq) do { __builtin_amdgcn_s_setprio(1); \
;     for (int m = 0; m < 4; ++m) for (int n = 0; n < 2; ++n) for (int k = 0; k < 2; ++k) \
;       acc[ai][bj][m][n] = __builtin_amdgcn_mfma_f32_16x16x32_bf16(At[m][k], Bq[n][k], acc[ai][bj][m][n], 0, 0, 0); \
;     __builtin_amdgcn_s_setprio(0); } while (0)
; #define WAIT_V(n) asm volatile("s_waitcnt vmcnt(" #n ")" ::: "memory")
; #define WAIT_L(n) asm volatile("s_waitcnt lgkmcnt(" #n ")" ::: "memory")
; #define BAR __builtin_amdgcn_s_barrier()
; #define SCHED __builtin_amdgcn_sched_barrier(0)
; template <class Epi>
; __device__ __forceinline__ void gemm_tile(const u16* __restrict__ A, const u16* __restrict__ Bt, int K,
;                                           int brow, int bcol, bool first, bool has_next, int nbrow, int nbcol, Epi epi) {
;     ...
;     LDA(At, 1, 1); STAGE(SA(1, 0), A, brow, t + 3);
;     BAR; WAIT_L(0); MMA(1, 0, At, B0); BAR; SCHED;
;     STAGE(SB(1, 1), Bt, bcol + HALF, t + 3);
;     WAIT_V(6); BAR; MMA(1, 1, At, B1); BAR;
;   }
;   { LDB(B0, 0, 0); LDA(At, 0, 0); STAGE(SA(1, 1), A, brow + HALF, nt - 1);
;     BAR; WAIT_L(0); MMA(0, 0, At, B0); BAR;
	ds_read_b128 v[192:195], v159 offset:49152
	ds_read_b128 v[196:199], v159 offset:50176
	ds_read_b128 v[200:203], v158 offset:49152
	ds_read_b128 v[204:207], v158 offset:50176
	ds_read_b128 v[208:211], v157 offset:49152
	ds_read_b128 v[212:215], v157 offset:50176
	ds_read_b128 v[216:219], v156 offset:49152
	ds_read_b128 v[220:223], v156 offset:50176
	global_load_lds_dwordx4 v[170:171], off
	v_add_u32_e32 v170, 0xa000, v153
	v_lshl_add_u64 v[240:241], v[246:247], 0, s[20:21]
	v_readfirstlane_b32 s3, v170
	s_mov_b32 m0, s3
	s_nop 0
	global_load_lds_dwordx4 v[240:241], off
	s_barrier
	s_waitcnt lgkmcnt(0)
	s_setprio 1
	s_waitcnt lgkmcnt(0)
	s_nop 0
	v_mfma_f32_16x16x32_bf16 v[60:63], v[192:195], v[176:179], v[60:63]
	v_mfma_f32_16x16x32_bf16 v[56:59], v[192:195], v[184:187], v[56:59]
	v_mfma_f32_16x16x32_bf16 v[52:55], v[200:203], v[176:179], v[52:55]
	v_mfma_f32_16x16x32_bf16 v[48:51], v[200:203], v[184:187], v[48:51]
	v_mfma_f32_16x16x32_bf16 v[44:47], v[208:211], v[176:179], v[44:47]
	v_mfma_f32_16x16x32_bf16 v[40:43], v[208:211], v[184:187], v[40:43]
	v_mfma_f32_16x16x32_bf16 v[36:39], v[216:219], v[176:179], v[36:39]
	v_mfma_f32_16x16x32_bf16 v[32:35], v[216:219], v[184:187], v[32:35]
	v_mfma_f32_16x16x32_bf16 v[60:63], v[196:199], v[180:183], v[60:63]
	v_mfma_f32_16x16x32_bf16 v[56:59], v[196:199], v[188:191], v[56:59]
	v_mfma_f32_16x16x32_bf16 v[52:55], v[204:207], v[180:183], v[52:55]
	v_mfma_f32_16x16x32_bf16 v[48:51], v[204:207], v[188:191], v[48:51]
	v_mfma_f32_16x16x32_bf16 v[44:47], v[212:215], v[180:183], v[44:47]
	v_mfma_f32_16x16x32_bf16 v[40:43], v[212:215], v[188:191], v[40:43]
	v_mfma_f32_16x16x32_bf16 v[36:39], v[220:223], v[180:183], v[36:39]
	v_mfma_f32_16x16x32_bf16 v[32:35], v[220:223], v[188:191], v[32:35]
	s_setprio 0
	s_barrier
	v_add_u32_e32 v171, s85, v155
	v_add_u32_e32 v172, 0x2000, v171
	v_readfirstlane_b32 s3, v171
	v_lshl_add_u64 v[176:177], v[248:249], 0, s[18:19]
	s_mov_b32 m0, s3
	v_readfirstlane_b32 s3, v172
	global_load_lds_dwordx4 v[176:177], off
	v_lshl_add_u64 v[176:177], v[250:251], 0, s[18:19]
	s_mov_b32 m0, s3
	s_nop 0
	global_load_lds_dwordx4 v[176:177], off
	s_waitcnt vmcnt(6)
	s_barrier
	s_setprio 1
	s_nop 0
	v_mfma_f32_16x16x32_bf16 v[28:31], v[192:195], v[224:227], v[28:31]
	v_mfma_f32_16x16x32_bf16 v[24:27], v[192:195], v[232:235], v[24:27]
	v_mfma_f32_16x16x32_bf16 v[20:23], v[200:203], v[224:227], v[20:23]
	v_mfma_f32_16x16x32_bf16 v[16:19], v[200:203], v[232:235], v[16:19]
	v_mfma_f32_16x16x32_bf16 v[12:15], v[208:211], v[224:227], v[12:15]
	v_mfma_f32_16x16x32_bf16 v[8:11], v[208:211], v[232:235], v[8:11]
	v_mfma_f32_16x16x32_bf16 v[4:7], v[216:219], v[224:227], v[4:7]
	v_mfma_f32_16x16x32_bf16 v[0:3], v[216:219], v[232:235], v[0:3]
	v_mfma_f32_16x16x32_bf16 v[28:31], v[196:199], v[228:231], v[28:31]
	v_mfma_f32_16x16x32_bf16 v[24:27], v[196:199], v[236:239], v[24:27]
	v_mfma_f32_16x16x32_bf16 v[20:23], v[204:207], v[228:231], v[20:23]
	v_mfma_f32_16x16x32_bf16 v[16:19], v[204:207], v[236:239], v[16:19]
	v_mfma_f32_16x16x32_bf16 v[12:15], v[212:215], v[228:231], v[12:15]
	v_mfma_f32_16x16x32_bf16 v[8:11], v[212:215], v[236:239], v[8:11]
	v_mfma_f32_16x16x32_bf16 v[4:7], v[220:223], v[228:231], v[4:7]
	v_mfma_f32_16x16x32_bf16 v[0:3], v[220:223], v[236:239], v[0:3]
	s_setprio 0
	s_add_i32 s1, s1, 2
	s_add_u32 s40, s40, 0x100
	s_addc_u32 s41, s41, 0
	s_cmp_lt_u32 s1, 12
	s_barrier
	s_cbranch_scc1 .LBB0_592
	s_add_u32 s36, s6, s36
	s_addc_u32 s37, s7, s37
	v_lshl_add_u64 v[208:209], s[36:37], 0, v[128:129]
	v_readfirstlane_b32 s1, v173
	v_lshl_add_u64 v[208:209], v[208:209], 0, s[22:23]
	s_mov_b32 m0, s1
	ds_read_b128 v[132:135], v164
	ds_read_b128 v[136:139], v164 offset:1024
	ds_read_b128 v[140:143], v164 offset:2048
	ds_read_b128 v[144:147], v164 offset:3072
	ds_read_b128 v[176:179], v159
	ds_read_b128 v[180:183], v159 offset:1024
	ds_read_b128 v[184:187], v158
	ds_read_b128 v[188:191], v158 offset:1024
	ds_read_b128 v[192:195], v157
	ds_read_b128 v[196:199], v157 offset:1024
	ds_read_b128 v[200:203], v156
	ds_read_b128 v[204:207], v156 offset:1024
	global_load_lds_dwordx4 v[208:209], off
	v_lshl_add_u64 v[208:209], s[36:37], 0, v[130:131]
	v_readfirstlane_b32 s1, v174
	v_lshl_add_u64 v[208:209], v[208:209], 0, s[22:23]
	s_mov_b32 m0, s1
	s_nop 0
	global_load_lds_dwordx4 v[208:209], off
	s_barrier
	s_waitcnt lgkmcnt(0)
	s_setprio 1
	s_waitcnt lgkmcnt(0)
	v_mfma_f32_16x16x32_bf16 v[124:127], v[176:179], v[132:135], v[124:127]
	v_mfma_f32_16x16x32_bf16 v[116:119], v[184:187], v[132:135], v[116:119]
	v_mfma_f32_16x16x32_bf16 v[108:111], v[192:195], v[132:135], v[108:111]
	v_mfma_f32_16x16x32_bf16 v[100:103], v[200:203], v[132:135], v[100:103]
	v_mfma_f32_16x16x32_bf16 v[124:127], v[180:183], v[136:139], v[124:127]
	v_mfma_f32_16x16x32_bf16 v[120:123], v[176:179], v[140:143], v[120:123]
	v_mfma_f32_16x16x32_bf16 v[116:119], v[188:191], v[136:139], v[116:119]
	v_mfma_f32_16x16x32_bf16 v[112:115], v[184:187], v[140:143], v[112:115]
	v_mfma_f32_16x16x32_bf16 v[108:111], v[196:199], v[136:139], v[108:111]
	v_mfma_f32_16x16x32_bf16 v[104:107], v[192:195], v[140:143], v[104:107]
	v_mfma_f32_16x16x32_bf16 v[100:103], v[204:207], v[136:139], v[100:103]
	v_mfma_f32_16x16x32_bf16 v[96:99], v[200:203], v[140:143], v[96:99]
	v_mfma_f32_16x16x32_bf16 v[208:211], v[180:183], v[144:147], v[120:123]
	v_mfma_f32_16x16x32_bf16 v[212:215], v[188:191], v[144:147], v[112:115]
	v_mfma_f32_16x16x32_bf16 v[216:219], v[196:199], v[144:147], v[104:107]
	v_mfma_f32_16x16x32_bf16 v[220:223], v[204:207], v[144:147], v[96:99]
	s_setprio 0
	s_barrier
; #define LDA(dst, b, h) for (int m = 0; m < 4; ++m) for (int k = 0; k < 2; ++k) \
;     dst[m][k] = *reinterpret_cast<const bf16x8*>((char*)SA(b, h) + lds_byte(wr * 64 + m * 16 + fr, k * 32 + fq * 8))
; #define LDB(dst, b, h) for (int n = 0; n < 2; ++n) for (int k = 0; k < 2; ++k) \
;     dst[n][k] = *reinterpret_cast<const bf16x8*>((char*)SB(b, h) + lds_byte(wc * 32 + n * 16 + fr, k * 32 + fq * 8))
; #define MMA(ai, bj, At, Bq) do { __builtin_amdgcn_s_setprio(1); \
;     for (int m = 0; m < 4; ++m) for (int n = 0; n < 2; ++n) for (int k = 0; k < 2; ++k) \
;       acc[ai][bj][m][n] = __builtin_amdgcn_mfma_f32_16x16x32_bf16(At[m][k], Bq[n][k], acc[ai][bj][m][n], 0, 0, 0); \
;     __builtin_amdgcn_s_setprio(0); } while (0)
; #define WAIT_V(n) asm volatile("s_waitcnt vmcnt(" #n ")" ::: "memory")
; #define WAIT_L(n) asm volatile("s_waitcnt lgkmcnt(" #n ")" ::: "memory")
; #define BAR __builtin_amdgcn_s_barrier()
; template <class Epi>
; __device__ __forceinline__ void gemm_tile(const u16* __restrict__ A, const u16* __restrict__ Bt, int K,
;                                           int brow, int bcol, bool first, bool has_next, int nbrow, int nbcol, Epi epi) {
;     ...
;     LDB(B1, 0, 1); BAR; WAIT_L(0); MMA(0, 1, At, B1); BAR;
;     LDA(At, 0, 1); WAIT_V(4); BAR; WAIT_L(0); MMA(1, 0, At, B0); MMA(1, 1, At, B1); BAR; }
;   { LDB(B0, 1, 0); LDA(At, 1, 0); WAIT_V(2); BAR; WAIT_L(0); MMA(0, 0, At, B0); BAR;
	s_nop 1
	ds_read_b128 v[96:99], v163
	ds_read_b128 v[104:107], v163 offset:1024
	ds_read_b128 v[112:115], v163 offset:2048
	ds_read_b128 v[120:123], v163 offset:3072
	s_barrier
	s_waitcnt lgkmcnt(0)
	s_setprio 1
	s_waitcnt lgkmcnt(0)
	v_mfma_f32_16x16x32_bf16 v[92:95], v[176:179], v[96:99], v[92:95]
	v_mfma_f32_16x16x32_bf16 v[84:87], v[184:187], v[96:99], v[84:87]
	v_mfma_f32_16x16x32_bf16 v[76:79], v[192:195], v[96:99], v[76:79]
	v_mfma_f32_16x16x32_bf16 v[68:71], v[200:203], v[96:99], v[68:71]
	v_mfma_f32_16x16x32_bf16 v[92:95], v[180:183], v[104:107], v[92:95]
	v_mfma_f32_16x16x32_bf16 v[88:91], v[176:179], v[112:115], v[88:91]
	v_mfma_f32_16x16x32_bf16 v[84:87], v[188:191], v[104:107], v[84:87]
	v_mfma_f32_16x16x32_bf16 v[80:83], v[184:187], v[112:115], v[80:83]
	v_mfma_f32_16x16x32_bf16 v[76:79], v[196:199], v[104:107], v[76:79]
	v_mfma_f32_16x16x32_bf16 v[72:75], v[192:195], v[112:115], v[72:75]
	v_mfma_f32_16x16x32_bf16 v[68:71], v[204:207], v[104:107], v[68:71]
	v_mfma_f32_16x16x32_bf16 v[64:67], v[200:203], v[112:115], v[64:67]
	v_mfma_f32_16x16x32_bf16 v[174:177], v[180:183], v[120:123], v[88:91]
	v_mfma_f32_16x16x32_bf16 v[178:181], v[188:191], v[120:123], v[80:83]
	v_mfma_f32_16x16x32_bf16 v[182:185], v[196:199], v[120:123], v[72:75]
	v_mfma_f32_16x16x32_bf16 v[186:189], v[204:207], v[120:123], v[64:67]
	s_setprio 0
	s_barrier
	s_nop 1
	ds_read_b128 v[64:67], v159 offset:16384
	ds_read_b128 v[72:75], v159 offset:17408
	ds_read_b128 v[80:83], v158 offset:16384
	ds_read_b128 v[88:91], v158 offset:17408
	ds_read_b128 v[190:193], v157 offset:16384
	ds_read_b128 v[194:197], v157 offset:17408
	ds_read_b128 v[198:201], v156 offset:16384
	ds_read_b128 v[202:205], v156 offset:17408
	s_waitcnt vmcnt(4)
	s_barrier
	s_waitcnt lgkmcnt(0)
	s_setprio 1
	s_waitcnt lgkmcnt(0)
	v_mfma_f32_16x16x32_bf16 v[60:63], v[64:67], v[132:135], v[60:63]
	v_mfma_f32_16x16x32_bf16 v[52:55], v[80:83], v[132:135], v[52:55]
	v_mfma_f32_16x16x32_bf16 v[44:47], v[190:193], v[132:135], v[44:47]
	v_mfma_f32_16x16x32_bf16 v[36:39], v[198:201], v[132:135], v[36:39]
	v_mfma_f32_16x16x32_bf16 v[60:63], v[72:75], v[136:139], v[60:63]
	v_mfma_f32_16x16x32_bf16 v[56:59], v[64:67], v[140:143], v[56:59]
	v_mfma_f32_16x16x32_bf16 v[52:55], v[88:91], v[136:139], v[52:55]
	v_mfma_f32_16x16x32_bf16 v[48:51], v[80:83], v[140:143], v[48:51]
	v_mfma_f32_16x16x32_bf16 v[44:47], v[194:197], v[136:139], v[44:47]
	v_mfma_f32_16x16x32_bf16 v[40:43], v[190:193], v[140:143], v[40:43]
	v_mfma_f32_16x16x32_bf16 v[36:39], v[202:205], v[136:139], v[36:39]
	v_mfma_f32_16x16x32_bf16 v[32:35], v[198:201], v[140:143], v[32:35]
	v_mfma_f32_16x16x32_bf16 v[224:227], v[72:75], v[144:147], v[56:59]
	v_mfma_f32_16x16x32_bf16 v[228:231], v[88:91], v[144:147], v[48:51]
	v_mfma_f32_16x16x32_bf16 v[232:235], v[194:197], v[144:147], v[40:43]
	v_mfma_f32_16x16x32_bf16 v[132:135], v[202:205], v[144:147], v[32:35]
	s_setprio 0
	s_setprio 1
	v_mfma_f32_16x16x32_bf16 v[28:31], v[64:67], v[96:99], v[28:31]
	v_mfma_f32_16x16x32_bf16 v[20:23], v[80:83], v[96:99], v[20:23]
	v_mfma_f32_16x16x32_bf16 v[12:15], v[190:193], v[96:99], v[12:15]
	v_mfma_f32_16x16x32_bf16 v[4:7], v[198:201], v[96:99], v[4:7]
	v_mfma_f32_16x16x32_bf16 v[28:31], v[72:75], v[104:107], v[28:31]
	v_mfma_f32_16x16x32_bf16 v[24:27], v[64:67], v[112:115], v[24:27]
	v_mfma_f32_16x16x32_bf16 v[20:23], v[88:91], v[104:107], v[20:23]
	v_mfma_f32_16x16x32_bf16 v[16:19], v[80:83], v[112:115], v[16:19]
	v_mfma_f32_16x16x32_bf16 v[12:15], v[194:197], v[104:107], v[12:15]
	v_mfma_f32_16x16x32_bf16 v[8:11], v[190:193], v[112:115], v[8:11]
	v_mfma_f32_16x16x32_bf16 v[4:7], v[202:205], v[104:107], v[4:7]
	v_mfma_f32_16x16x32_bf16 v[0:3], v[198:201], v[112:115], v[0:3]
	v_mfma_f32_16x16x32_bf16 v[136:139], v[72:75], v[120:123], v[24:27]
	v_mfma_f32_16x16x32_bf16 v[140:143], v[88:91], v[120:123], v[16:19]
	v_mfma_f32_16x16x32_bf16 v[144:147], v[194:197], v[120:123], v[8:11]
	v_mfma_f32_16x16x32_bf16 v[190:193], v[202:205], v[120:123], v[0:3]
	s_setprio 0
	s_barrier
	s_nop 1
	ds_read_b128 v[0:3], v161
	ds_read_b128 v[8:11], v161 offset:1024
	ds_read_b128 v[194:197], v161 offset:2048
	ds_read_b128 v[198:201], v161 offset:3072
	ds_read_b128 v[16:19], v159 offset:32768
	ds_read_b128 v[24:27], v159 offset:33792
	ds_read_b128 v[32:35], v158 offset:32768
	ds_read_b128 v[40:43], v158 offset:33792
	ds_read_b128 v[48:51], v157 offset:32768
	ds_read_b128 v[56:59], v157 offset:33792
	ds_read_b128 v[202:205], v156 offset:32768
	ds_read_b128 v[236:239], v156 offset:33792
	s_waitcnt vmcnt(2)
	s_barrier
; #define LDA(dst, b, h) for (int m = 0; m < 4; ++m) for (int k = 0; k < 2; ++k) \
;     dst[m][k] = *reinterpret_cast<const bf16x8*>((char*)SA(b, h) + lds_byte(wr * 64 + m * 16 + fr, k * 32 + fq * 8))
; #define LDB(dst, b, h) for (int n = 0; n < 2; ++n) for (int k = 0; k < 2; ++k) \
;     dst[n][k] = *reinterpret_cast<const bf16x8*>((char*)SB(b, h) + lds_byte(wc * 32 + n * 16 + fr, k * 32 + fq * 8))
; #define MMA(ai, bj, At, Bq) do { __builtin_amdgcn_s_setprio(1); \
;     for (int m = 0; m < 4; ++m) for (int n = 0; n < 2; ++n) for (int k = 0; k < 2; ++k) \
;       acc[ai][bj][m][n] = __builtin_amdgcn_mfma_f32_16x16x32_bf16(At[m][k], Bq[n][k], acc[ai][bj][m][n], 0, 0, 0); \
;     __builtin_amdgcn_s_setprio(0); } while (0)
; #define WAIT_V(n) asm volatile("s_waitcnt vmcnt(" #n ")" ::: "memory")
; #define WAIT_L(n) asm volatile("s_waitcnt lgkmcnt(" #n ")" ::: "memory")
; #define BAR __builtin_amdgcn_s_barrier()
; template <class Epi>
; __device__ __forceinline__ void gemm_tile(const u16* __restrict__ A, const u16* __restrict__ Bt, int K,
;                                           int brow, int bcol, bool first, bool has_next, int nbrow, int nbcol, Epi epi) {
;     ...
;   { LDB(B0, 1, 0); LDA(At, 1, 0); WAIT_V(2); BAR; WAIT_L(0); MMA(0, 0, At, B0); BAR;
;     LDB(B1, 1, 1); WAIT_V(0); BAR; WAIT_L(0); MMA(0, 1, At, B1); BAR;
;     LDA(At, 1, 1); BAR; WAIT_L(0); MMA(1, 0, At, B0); MMA(1, 1, At, B1); BAR; }
;   if (wr == 0) BAR;
	s_waitcnt lgkmcnt(0)
	s_setprio 1
	s_waitcnt lgkmcnt(0)
	v_mfma_f32_16x16x32_bf16 v[64:67], v[16:19], v[0:3], v[124:127]
	v_mfma_f32_16x16x32_bf16 v[120:123], v[24:27], v[8:11], v[64:67]
	v_mfma_f32_16x16x32_bf16 v[64:67], v[16:19], v[194:197], v[208:211]
	v_mfma_f32_16x16x32_bf16 v[112:115], v[24:27], v[198:201], v[64:67]
	v_mfma_f32_16x16x32_bf16 v[64:67], v[32:35], v[0:3], v[116:119]
	v_mfma_f32_16x16x32_bf16 v[104:107], v[40:43], v[8:11], v[64:67]
	v_mfma_f32_16x16x32_bf16 v[64:67], v[32:35], v[194:197], v[212:215]
	v_mfma_f32_16x16x32_bf16 v[96:99], v[40:43], v[198:201], v[64:67]
	v_mfma_f32_16x16x32_bf16 v[64:67], v[48:51], v[0:3], v[108:111]
	v_mfma_f32_16x16x32_bf16 v[88:91], v[56:59], v[8:11], v[64:67]
	v_mfma_f32_16x16x32_bf16 v[64:67], v[48:51], v[194:197], v[216:219]
	v_mfma_f32_16x16x32_bf16 v[80:83], v[56:59], v[198:201], v[64:67]
	v_mfma_f32_16x16x32_bf16 v[64:67], v[202:205], v[0:3], v[100:103]
	v_mfma_f32_16x16x32_bf16 v[72:75], v[236:239], v[8:11], v[64:67]
	v_mfma_f32_16x16x32_bf16 v[64:67], v[202:205], v[194:197], v[220:223]
	v_mfma_f32_16x16x32_bf16 v[64:67], v[236:239], v[198:201], v[64:67]
	s_setprio 0
	s_barrier
	ds_read_b128 v[206:209], v160
	ds_read_b128 v[210:213], v160 offset:1024
	ds_read_b128 v[214:217], v160 offset:2048
	ds_read_b128 v[218:221], v160 offset:3072
	s_waitcnt vmcnt(0)
	s_barrier
	s_waitcnt lgkmcnt(0)
	s_setprio 1
	s_waitcnt lgkmcnt(0)
	v_mfma_f32_16x16x32_bf16 v[92:95], v[16:19], v[206:209], v[92:95]
	v_mfma_f32_16x16x32_bf16 v[16:19], v[16:19], v[214:217], v[174:177]
	v_mfma_f32_16x16x32_bf16 v[116:119], v[24:27], v[218:221], v[16:19]
	v_mfma_f32_16x16x32_bf16 v[16:19], v[32:35], v[206:209], v[84:87]
	v_mfma_f32_16x16x32_bf16 v[108:111], v[40:43], v[210:213], v[16:19]
	v_mfma_f32_16x16x32_bf16 v[16:19], v[32:35], v[214:217], v[178:181]
	v_mfma_f32_16x16x32_bf16 v[100:103], v[40:43], v[218:221], v[16:19]
	v_mfma_f32_16x16x32_bf16 v[16:19], v[48:51], v[206:209], v[76:79]
	v_mfma_f32_16x16x32_bf16 v[124:127], v[24:27], v[210:213], v[92:95]
	v_mfma_f32_16x16x32_bf16 v[92:95], v[56:59], v[210:213], v[16:19]
	v_mfma_f32_16x16x32_bf16 v[16:19], v[48:51], v[214:217], v[182:185]
	v_mfma_f32_16x16x32_bf16 v[84:87], v[56:59], v[218:221], v[16:19]
	v_mfma_f32_16x16x32_bf16 v[16:19], v[202:205], v[206:209], v[68:71]
	v_mfma_f32_16x16x32_bf16 v[76:79], v[236:239], v[210:213], v[16:19]
	v_mfma_f32_16x16x32_bf16 v[16:19], v[202:205], v[214:217], v[186:189]
	v_mfma_f32_16x16x32_bf16 v[68:71], v[236:239], v[218:221], v[16:19]
	s_setprio 0
	s_barrier
	ds_read_b128 v[174:177], v159 offset:49152
	ds_read_b128 v[178:181], v159 offset:50176
	ds_read_b128 v[182:185], v158 offset:49152
	ds_read_b128 v[158:161], v158 offset:50176
	ds_read_b128 v[186:189], v157 offset:49152
	ds_read_b128 v[202:205], v157 offset:50176
	ds_read_b128 v[236:239], v156 offset:49152
	ds_read_b128 v[240:243], v156 offset:50176
	s_barrier
	s_waitcnt lgkmcnt(0)
	s_setprio 1
	s_waitcnt lgkmcnt(0)
	v_mfma_f32_16x16x32_bf16 v[16:19], v[174:177], v[0:3], v[60:63]
	v_mfma_f32_16x16x32_bf16 v[56:59], v[178:181], v[8:11], v[16:19]
	v_mfma_f32_16x16x32_bf16 v[16:19], v[174:177], v[194:197], v[224:227]
	v_mfma_f32_16x16x32_bf16 v[48:51], v[178:181], v[198:201], v[16:19]
	v_mfma_f32_16x16x32_bf16 v[16:19], v[182:185], v[0:3], v[52:55]
	v_mfma_f32_16x16x32_bf16 v[40:43], v[158:161], v[8:11], v[16:19]
	v_mfma_f32_16x16x32_bf16 v[16:19], v[182:185], v[194:197], v[228:231]
	v_mfma_f32_16x16x32_bf16 v[32:35], v[158:161], v[198:201], v[16:19]
	v_mfma_f32_16x16x32_bf16 v[16:19], v[186:189], v[0:3], v[44:47]
	v_mfma_f32_16x16x32_bf16 v[0:3], v[236:239], v[0:3], v[36:39]
	v_mfma_f32_16x16x32_bf16 v[24:27], v[202:205], v[8:11], v[16:19]
	v_mfma_f32_16x16x32_bf16 v[16:19], v[186:189], v[194:197], v[232:235]
	v_mfma_f32_16x16x32_bf16 v[8:11], v[240:243], v[8:11], v[0:3]
	v_mfma_f32_16x16x32_bf16 v[0:3], v[236:239], v[194:197], v[132:135]
	v_mfma_f32_16x16x32_bf16 v[16:19], v[202:205], v[198:201], v[16:19]
	v_mfma_f32_16x16x32_bf16 v[0:3], v[240:243], v[198:201], v[0:3]
	s_setprio 0
	s_setprio 1
	v_mfma_f32_16x16x32_bf16 v[28:31], v[174:177], v[206:209], v[28:31]
	v_mfma_f32_16x16x32_bf16 v[60:63], v[178:181], v[210:213], v[28:31]
	v_mfma_f32_16x16x32_bf16 v[28:31], v[174:177], v[214:217], v[136:139]
	v_mfma_f32_16x16x32_bf16 v[20:23], v[182:185], v[206:209], v[20:23]
	v_mfma_f32_16x16x32_bf16 v[12:15], v[186:189], v[206:209], v[12:15]
	v_mfma_f32_16x16x32_bf16 v[52:55], v[178:181], v[218:221], v[28:31]
	v_mfma_f32_16x16x32_bf16 v[44:47], v[158:161], v[210:213], v[20:23]
	v_mfma_f32_16x16x32_bf16 v[20:23], v[182:185], v[214:217], v[140:143]
	v_mfma_f32_16x16x32_bf16 v[28:31], v[202:205], v[210:213], v[12:15]
	v_mfma_f32_16x16x32_bf16 v[12:15], v[186:189], v[214:217], v[144:147]
	v_mfma_f32_16x16x32_bf16 v[4:7], v[236:239], v[206:209], v[4:7]
	v_mfma_f32_16x16x32_bf16 v[36:39], v[158:161], v[218:221], v[20:23]
	v_mfma_f32_16x16x32_bf16 v[20:23], v[202:205], v[218:221], v[12:15]
	v_mfma_f32_16x16x32_bf16 v[12:15], v[240:243], v[210:213], v[4:7]
	v_mfma_f32_16x16x32_bf16 v[4:7], v[236:239], v[214:217], v[190:193]
	v_mfma_f32_16x16x32_bf16 v[4:7], v[240:243], v[218:221], v[4:7]
	s_setprio 0
	v_cmp_gt_u32_e32 vcc, s61, v148
	s_barrier
	s_and_saveexec_b64 s[36:37], vcc
	s_cbranch_execz .LBB0_595
	s_barrier

; #define LDA(dst, b, h) for (int m = 0; m < 4; ++m) for (int k = 0; k < 2; ++k) \
;     dst[m][k] = *reinterpret_cast<const bf16x8*>((char*)SA(b, h) + lds_byte(wr * 64 + m * 16 + fr, k * 32 + fq * 8))
; #define LDB(dst, b, h) for (int n = 0; n < 2; ++n) for (int k = 0; k < 2; ++k) \
;     dst[n][k] = *reinterpret_cast<const bf16x8*>((char*)SB(b, h) + lds_byte(wc * 32 + n * 16 + fr, k * 32 + fq * 8))
; #define MMA(ai, bj, At, Bq) do { __builtin_amdgcn_s_setprio(1); \
;     for (int m = 0; m < 4; ++m) for (int n = 0; n < 2; ++n) for (int k = 0; k < 2; ++k) \
;       acc[ai][bj][m][n] = __builtin_amdgcn_mfma_f32_16x16x32_bf16(At[m][k], Bq[n][k], acc[ai][bj][m][n], 0, 0, 0); \
;     __builtin_amdgcn_s_setprio(0); } while (0)
; #define WAIT_L(n) asm volatile("s_waitcnt lgkmcnt(" #n ")" ::: "memory")
; #define BAR __builtin_amdgcn_s_barrier()
; #define SCHED __builtin_amdgcn_sched_barrier(0)
; template <class Epi>
; __device__ __forceinline__ void gemm_tile(const u16* __restrict__ A, const u16* __restrict__ Bt, int K,
;                                           int brow, int bcol, bool first, bool has_next, int nbrow, int nbcol, Epi epi) {
;     ...
;     LDB(B0, 0, 0); SCHED; LDA(At, 0, 0); STAGE(SA(1, 1), A, brow + HALF, t + 1);
;     WAIT_L(8); BAR; WAIT_L(0); MMA(0, 0, At, B0); BAR; SCHED;
;     LDB(B1, 0, 1); STAGE(SB(0, 0), Bt, bcol, t + 2);
;     BAR; WAIT_L(0); MMA(0, 1, At, B1); BAR;
;     LDA(At, 0, 1); STAGE(SA(0, 0), A, brow, t + 2);
;     BAR; WAIT_L(0); MMA(1, 0, At, B0); BAR; SCHED;
.LBB0_663:
	ds_read_b128 v[172:175], v169
	ds_read_b128 v[180:183], v169 offset:1024
	ds_read_b128 v[184:187], v169 offset:2048
	ds_read_b128 v[188:191], v169 offset:3072
	v_add_u32_e32 v178, 0xc000, v159
	v_lshl_add_u64 v[240:241], s[18:19], 0, v[148:149]
	v_readfirstlane_b32 s21, v178
	v_add_u32_e32 v179, 0xe000, v159
	v_lshl_add_u64 v[170:171], v[240:241], 0, s[8:9]
	s_mov_b32 m0, s21
	v_lshl_add_u64 v[242:243], s[18:19], 0, v[150:151]
	v_readfirstlane_b32 s21, v179
	ds_read_b128 v[192:195], v165
	ds_read_b128 v[196:199], v165 offset:1024
	ds_read_b128 v[200:203], v164
	ds_read_b128 v[204:207], v164 offset:1024
	ds_read_b128 v[208:211], v163
	ds_read_b128 v[212:215], v163 offset:1024
	ds_read_b128 v[216:219], v162
	ds_read_b128 v[220:223], v162 offset:1024
	global_load_lds_dwordx4 v[170:171], off
	v_lshl_add_u64 v[170:171], v[242:243], 0, s[8:9]
	s_mov_b32 m0, s21
	s_nop 0
	global_load_lds_dwordx4 v[170:171], off
	s_waitcnt lgkmcnt(8)
	s_barrier
	s_waitcnt lgkmcnt(0)
	s_setprio 1
	s_waitcnt lgkmcnt(0)
	v_mfma_f32_16x16x32_bf16 v[124:127], v[192:195], v[172:175], v[124:127]
	v_mfma_f32_16x16x32_bf16 v[120:123], v[192:195], v[184:187], v[120:123]
	v_mfma_f32_16x16x32_bf16 v[116:119], v[200:203], v[172:175], v[116:119]
	v_mfma_f32_16x16x32_bf16 v[112:115], v[200:203], v[184:187], v[112:115]
	v_mfma_f32_16x16x32_bf16 v[108:111], v[208:211], v[172:175], v[108:111]
	v_mfma_f32_16x16x32_bf16 v[104:107], v[208:211], v[184:187], v[104:107]
	v_mfma_f32_16x16x32_bf16 v[100:103], v[216:219], v[172:175], v[100:103]
	v_mfma_f32_16x16x32_bf16 v[96:99], v[216:219], v[184:187], v[96:99]
	v_mfma_f32_16x16x32_bf16 v[124:127], v[196:199], v[180:183], v[124:127]
	v_mfma_f32_16x16x32_bf16 v[120:123], v[196:199], v[188:191], v[120:123]
	v_mfma_f32_16x16x32_bf16 v[116:119], v[204:207], v[180:183], v[116:119]
	v_mfma_f32_16x16x32_bf16 v[112:115], v[204:207], v[188:191], v[112:115]
	v_mfma_f32_16x16x32_bf16 v[108:111], v[212:215], v[180:183], v[108:111]
	v_mfma_f32_16x16x32_bf16 v[104:107], v[212:215], v[188:191], v[104:107]
	v_mfma_f32_16x16x32_bf16 v[100:103], v[220:223], v[180:183], v[100:103]
	v_mfma_f32_16x16x32_bf16 v[96:99], v[220:223], v[188:191], v[96:99]
	s_setprio 0
	s_barrier
	v_lshl_add_u64 v[244:245], s[18:19], 0, v[136:137]
	v_readfirstlane_b32 s21, v160
	v_lshl_add_u64 v[170:171], v[244:245], 0, s[10:11]
	s_mov_b32 m0, s21
	ds_read_b128 v[224:227], v168
	ds_read_b128 v[228:231], v168 offset:1024
	ds_read_b128 v[232:235], v168 offset:2048
	ds_read_b128 v[236:239], v168 offset:3072
	global_load_lds_dwordx4 v[170:171], off
	v_add_u32_e32 v170, 0x2000, v160
	v_lshl_add_u64 v[246:247], s[18:19], 0, v[138:139]
	v_readfirstlane_b32 s21, v170
	v_lshl_add_u64 v[176:177], v[246:247], 0, s[10:11]
	s_mov_b32 m0, s21
	s_nop 0
	global_load_lds_dwordx4 v[176:177], off
	s_barrier
	s_waitcnt lgkmcnt(0)
	s_setprio 1
	s_waitcnt lgkmcnt(0)
	s_nop 0
	v_mfma_f32_16x16x32_bf16 v[92:95], v[192:195], v[224:227], v[92:95]
	v_mfma_f32_16x16x32_bf16 v[88:91], v[192:195], v[232:235], v[88:91]
	v_mfma_f32_16x16x32_bf16 v[84:87], v[200:203], v[224:227], v[84:87]
	v_mfma_f32_16x16x32_bf16 v[80:83], v[200:203], v[232:235], v[80:83]
	v_mfma_f32_16x16x32_bf16 v[76:79], v[208:211], v[224:227], v[76:79]
	v_mfma_f32_16x16x32_bf16 v[72:75], v[208:211], v[232:235], v[72:75]
	v_mfma_f32_16x16x32_bf16 v[68:71], v[216:219], v[224:227], v[68:71]
	v_mfma_f32_16x16x32_bf16 v[64:67], v[216:219], v[232:235], v[64:67]
	v_mfma_f32_16x16x32_bf16 v[92:95], v[196:199], v[228:231], v[92:95]
	v_mfma_f32_16x16x32_bf16 v[88:91], v[196:199], v[236:239], v[88:91]
	v_mfma_f32_16x16x32_bf16 v[84:87], v[204:207], v[228:231], v[84:87]
	v_mfma_f32_16x16x32_bf16 v[80:83], v[204:207], v[236:239], v[80:83]
	v_mfma_f32_16x16x32_bf16 v[76:79], v[212:215], v[228:231], v[76:79]
	v_mfma_f32_16x16x32_bf16 v[72:75], v[212:215], v[236:239], v[72:75]
	v_mfma_f32_16x16x32_bf16 v[68:71], v[220:223], v[228:231], v[68:71]
	v_mfma_f32_16x16x32_bf16 v[64:67], v[220:223], v[236:239], v[64:67]
	s_setprio 0
	v_lshl_add_u64 v[248:249], s[18:19], 0, v[140:141]
	v_readfirstlane_b32 s21, v159
	v_lshl_add_u64 v[176:177], v[248:249], 0, s[12:13]
	s_mov_b32 m0, s21
	v_lshl_add_u64 v[250:251], s[18:19], 0, v[142:143]
	v_readfirstlane_b32 s21, v158
	s_barrier
	ds_read_b128 v[192:195], v165 offset:16384
	ds_read_b128 v[196:199], v165 offset:17408
	ds_read_b128 v[200:203], v164 offset:16384
	ds_read_b128 v[204:207], v164 offset:17408
	ds_read_b128 v[208:211], v163 offset:16384
	ds_read_b128 v[212:215], v163 offset:17408
	ds_read_b128 v[216:219], v162 offset:16384
	ds_read_b128 v[220:223], v162 offset:17408
	global_load_lds_dwordx4 v[176:177], off
	v_lshl_add_u64 v[176:177], v[250:251], 0, s[12:13]
	s_mov_b32 m0, s21
	s_nop 0
	global_load_lds_dwordx4 v[176:177], off
	s_barrier
	s_waitcnt lgkmcnt(0)
	s_setprio 1
	s_waitcnt lgkmcnt(0)
	s_nop 0
	v_mfma_f32_16x16x32_bf16 v[60:63], v[192:195], v[172:175], v[60:63]
	v_mfma_f32_16x16x32_bf16 v[56:59], v[192:195], v[184:187], v[56:59]
	v_mfma_f32_16x16x32_bf16 v[52:55], v[200:203], v[172:175], v[52:55]
	v_mfma_f32_16x16x32_bf16 v[48:51], v[200:203], v[184:187], v[48:51]
	v_mfma_f32_16x16x32_bf16 v[44:47], v[208:211], v[172:175], v[44:47]
	v_mfma_f32_16x16x32_bf16 v[40:43], v[208:211], v[184:187], v[40:43]
	v_mfma_f32_16x16x32_bf16 v[36:39], v[216:219], v[172:175], v[36:39]
	v_mfma_f32_16x16x32_bf16 v[32:35], v[216:219], v[184:187], v[32:35]
	v_mfma_f32_16x16x32_bf16 v[60:63], v[196:199], v[180:183], v[60:63]
	v_mfma_f32_16x16x32_bf16 v[56:59], v[196:199], v[188:191], v[56:59]
	v_mfma_f32_16x16x32_bf16 v[52:55], v[204:207], v[180:183], v[52:55]
	v_mfma_f32_16x16x32_bf16 v[48:51], v[204:207], v[188:191], v[48:51]
	v_mfma_f32_16x16x32_bf16 v[44:47], v[212:215], v[180:183], v[44:47]
	v_mfma_f32_16x16x32_bf16 v[40:43], v[212:215], v[188:191], v[40:43]
	v_mfma_f32_16x16x32_bf16 v[36:39], v[220:223], v[180:183], v[36:39]
	v_mfma_f32_16x16x32_bf16 v[32:35], v[220:223], v[188:191], v[32:35]
	s_setprio 0
	s_barrier
; #define LDA(dst, b, h) for (int m = 0; m < 4; ++m) for (int k = 0; k < 2; ++k) \
;     dst[m][k] = *reinterpret_cast<const bf16x8*>((char*)SA(b, h) + lds_byte(wr * 64 + m * 16 + fr, k * 32 + fq * 8))
; #define LDB(dst, b, h) for (int n = 0; n < 2; ++n) for (int k = 0; k < 2; ++k) \
;     dst[n][k] = *reinterpret_cast<const bf16x8*>((char*)SB(b, h) + lds_byte(wc * 32 + n * 16 + fr, k * 32 + fq * 8))
; #define MMA(ai, bj, At, Bq) do { __builtin_amdgcn_s_setprio(1); \
;     for (int m = 0; m < 4; ++m) for (int n = 0; n < 2; ++n) for (int k = 0; k < 2; ++k) \
;       acc[ai][bj][m][n] = __builtin_amdgcn_mfma_f32_16x16x32_bf16(At[m][k], Bq[n][k], acc[ai][bj][m][n], 0, 0, 0); \
;     __builtin_amdgcn_s_setprio(0); } while (0)
; #define WAIT_V(n) asm volatile("s_waitcnt vmcnt(" #n ")" ::: "memory")
; #define WAIT_L(n) asm volatile("s_waitcnt lgkmcnt(" #n ")" ::: "memory")
; #define BAR __builtin_amdgcn_s_barrier()
; #define SCHED __builtin_amdgcn_sched_barrier(0)
; template <class Epi>
; __device__ __forceinline__ void gemm_tile(const u16* __restrict__ A, const u16* __restrict__ Bt, int K,
;                                           int brow, int bcol, bool first, bool has_next, int nbrow, int nbcol, Epi epi) {
;     ...
;     STAGE(SB(0, 1), Bt, bcol + HALF, t + 2);
;     WAIT_V(6); BAR; MMA(1, 1, At, B1); BAR;
;     LDB(B0, 1, 0); SCHED; LDA(At, 1, 0); STAGE(SA(0, 1), A, brow + HALF, t + 2);
;     WAIT_L(8); BAR; WAIT_L(0); MMA(0, 0, At, B0); BAR; SCHED;
;     LDB(B1, 1, 1); STAGE(SB(1, 0), Bt, bcol, t + 3);
;     BAR; WAIT_L(0); MMA(0, 1, At, B1); BAR;
;     LDA(At, 1, 1); STAGE(SA(1, 0), A, brow, t + 3);
	v_lshl_add_u64 v[252:253], s[18:19], 0, v[144:145]
	v_readfirstlane_b32 s21, v157
	v_add_u32_e32 v171, 0x2000, v157
	v_lshl_add_u64 v[172:173], v[252:253], 0, s[10:11]
	s_mov_b32 m0, s21
	v_lshl_add_u64 v[152:153], s[18:19], 0, v[146:147]
	v_readfirstlane_b32 s21, v171
	global_load_lds_dwordx4 v[172:173], off
	v_lshl_add_u64 v[172:173], v[152:153], 0, s[10:11]
	s_mov_b32 m0, s21
	s_nop 0
	global_load_lds_dwordx4 v[172:173], off
	s_waitcnt vmcnt(6)
	s_barrier
	s_setprio 1
	v_mfma_f32_16x16x32_bf16 v[28:31], v[192:195], v[224:227], v[28:31]
	v_mfma_f32_16x16x32_bf16 v[24:27], v[192:195], v[232:235], v[24:27]
	v_mfma_f32_16x16x32_bf16 v[20:23], v[200:203], v[224:227], v[20:23]
	v_mfma_f32_16x16x32_bf16 v[16:19], v[200:203], v[232:235], v[16:19]
	v_mfma_f32_16x16x32_bf16 v[12:15], v[208:211], v[224:227], v[12:15]
	v_mfma_f32_16x16x32_bf16 v[8:11], v[208:211], v[232:235], v[8:11]
	v_mfma_f32_16x16x32_bf16 v[4:7], v[216:219], v[224:227], v[4:7]
	v_mfma_f32_16x16x32_bf16 v[0:3], v[216:219], v[232:235], v[0:3]
	v_mfma_f32_16x16x32_bf16 v[28:31], v[196:199], v[228:231], v[28:31]
	v_mfma_f32_16x16x32_bf16 v[24:27], v[196:199], v[236:239], v[24:27]
	v_mfma_f32_16x16x32_bf16 v[20:23], v[204:207], v[228:231], v[20:23]
	v_mfma_f32_16x16x32_bf16 v[16:19], v[204:207], v[236:239], v[16:19]
	v_mfma_f32_16x16x32_bf16 v[12:15], v[212:215], v[228:231], v[12:15]
	v_mfma_f32_16x16x32_bf16 v[8:11], v[212:215], v[236:239], v[8:11]
	v_mfma_f32_16x16x32_bf16 v[4:7], v[220:223], v[228:231], v[4:7]
	v_mfma_f32_16x16x32_bf16 v[0:3], v[220:223], v[236:239], v[0:3]
	s_setprio 0
	s_barrier
	ds_read_b128 v[180:183], v167
	ds_read_b128 v[184:187], v167 offset:1024
	ds_read_b128 v[188:191], v167 offset:2048
	ds_read_b128 v[192:195], v167 offset:3072
	v_readfirstlane_b32 s21, v156
	v_lshl_add_u64 v[172:173], v[240:241], 0, s[12:13]
	s_mov_b32 m0, s21
	v_readfirstlane_b32 s21, v130
	ds_read_b128 v[174:177], v165 offset:32768
	ds_read_b128 v[196:199], v165 offset:33792
	ds_read_b128 v[200:203], v164 offset:32768
	ds_read_b128 v[204:207], v164 offset:33792
	ds_read_b128 v[208:211], v163 offset:32768
	ds_read_b128 v[212:215], v163 offset:33792
	ds_read_b128 v[216:219], v162 offset:32768
	ds_read_b128 v[220:223], v162 offset:33792
	global_load_lds_dwordx4 v[172:173], off
	v_lshl_add_u64 v[172:173], v[242:243], 0, s[12:13]
	s_mov_b32 m0, s21
	s_nop 0
	global_load_lds_dwordx4 v[172:173], off
	s_waitcnt lgkmcnt(8)
	s_barrier
	s_waitcnt lgkmcnt(0)
	s_setprio 1
	s_waitcnt lgkmcnt(0)
	v_mfma_f32_16x16x32_bf16 v[124:127], v[174:177], v[180:183], v[124:127]
	v_mfma_f32_16x16x32_bf16 v[120:123], v[174:177], v[188:191], v[120:123]
	v_mfma_f32_16x16x32_bf16 v[116:119], v[200:203], v[180:183], v[116:119]
	v_mfma_f32_16x16x32_bf16 v[112:115], v[200:203], v[188:191], v[112:115]
	v_mfma_f32_16x16x32_bf16 v[108:111], v[208:211], v[180:183], v[108:111]
	v_mfma_f32_16x16x32_bf16 v[104:107], v[208:211], v[188:191], v[104:107]
	v_mfma_f32_16x16x32_bf16 v[100:103], v[216:219], v[180:183], v[100:103]
	v_mfma_f32_16x16x32_bf16 v[96:99], v[216:219], v[188:191], v[96:99]
	v_mfma_f32_16x16x32_bf16 v[124:127], v[196:199], v[184:187], v[124:127]
	v_mfma_f32_16x16x32_bf16 v[120:123], v[196:199], v[192:195], v[120:123]
	v_mfma_f32_16x16x32_bf16 v[116:119], v[204:207], v[184:187], v[116:119]
	v_mfma_f32_16x16x32_bf16 v[112:115], v[204:207], v[192:195], v[112:115]
	v_mfma_f32_16x16x32_bf16 v[108:111], v[212:215], v[184:187], v[108:111]
	v_mfma_f32_16x16x32_bf16 v[104:107], v[212:215], v[192:195], v[104:107]
	v_mfma_f32_16x16x32_bf16 v[100:103], v[220:223], v[184:187], v[100:103]
	v_mfma_f32_16x16x32_bf16 v[96:99], v[220:223], v[192:195], v[96:99]
	s_setprio 0
	s_barrier
	v_add_u32_e32 v172, s84, v161
	v_add_u32_e32 v173, 0x2000, v172
	v_readfirstlane_b32 s21, v172
	v_lshl_add_u64 v[240:241], v[244:245], 0, s[14:15]
	s_mov_b32 m0, s21
	v_readfirstlane_b32 s21, v173
	ds_read_b128 v[224:227], v166
	ds_read_b128 v[228:231], v166 offset:1024
	ds_read_b128 v[232:235], v166 offset:2048
	ds_read_b128 v[236:239], v166 offset:3072
	global_load_lds_dwordx4 v[240:241], off
	v_lshl_add_u64 v[240:241], v[246:247], 0, s[14:15]
	s_mov_b32 m0, s21
	s_nop 0
	global_load_lds_dwordx4 v[240:241], off
	s_barrier
	s_waitcnt lgkmcnt(0)
	s_setprio 1
	s_waitcnt lgkmcnt(0)
	v_mfma_f32_16x16x32_bf16 v[92:95], v[174:177], v[224:227], v[92:95]
	v_mfma_f32_16x16x32_bf16 v[88:91], v[174:177], v[232:235], v[88:91]
	v_mfma_f32_16x16x32_bf16 v[84:87], v[200:203], v[224:227], v[84:87]
	v_mfma_f32_16x16x32_bf16 v[80:83], v[200:203], v[232:235], v[80:83]
	v_mfma_f32_16x16x32_bf16 v[76:79], v[208:211], v[224:227], v[76:79]
	v_mfma_f32_16x16x32_bf16 v[72:75], v[208:211], v[232:235], v[72:75]
	v_mfma_f32_16x16x32_bf16 v[68:71], v[216:219], v[224:227], v[68:71]
	v_mfma_f32_16x16x32_bf16 v[64:67], v[216:219], v[232:235], v[64:67]
	v_mfma_f32_16x16x32_bf16 v[92:95], v[196:199], v[228:231], v[92:95]
	v_mfma_f32_16x16x32_bf16 v[88:91], v[196:199], v[236:239], v[88:91]
	v_mfma_f32_16x16x32_bf16 v[84:87], v[204:207], v[228:231], v[84:87]
	v_mfma_f32_16x16x32_bf16 v[80:83], v[204:207], v[236:239], v[80:83]
	v_mfma_f32_16x16x32_bf16 v[76:79], v[212:215], v[228:231], v[76:79]
	v_mfma_f32_16x16x32_bf16 v[72:75], v[212:215], v[236:239], v[72:75]
	v_mfma_f32_16x16x32_bf16 v[68:71], v[220:223], v[228:231], v[68:71]
	v_mfma_f32_16x16x32_bf16 v[64:67], v[220:223], v[236:239], v[64:67]
	s_setprio 0
	v_add_u32_e32 v174, 0x8000, v159
	v_add_u32_e32 v175, 0xa000, v159
	v_readfirstlane_b32 s21, v174
	v_lshl_add_u64 v[176:177], v[248:249], 0, s[16:17]
	s_mov_b32 m0, s21
	v_readfirstlane_b32 s21, v175
	s_barrier
; #define LDA(dst, b, h) for (int m = 0; m < 4; ++m) for (int k = 0; k < 2; ++k) \
;     dst[m][k] = *reinterpret_cast<const bf16x8*>((char*)SA(b, h) + lds_byte(wr * 64 + m * 16 + fr, k * 32 + fq * 8))
; #define LDB(dst, b, h) for (int n = 0; n < 2; ++n) for (int k = 0; k < 2; ++k) \
;     dst[n][k] = *reinterpret_cast<const bf16x8*>((char*)SB(b, h) + lds_byte(wc * 32 + n * 16 + fr, k * 32 + fq * 8))
; #define MMA(ai, bj, At, Bq) do { __builtin_amdgcn_s_setprio(1); \
;     for (int m = 0; m < 4; ++m) for (int n = 0; n < 2; ++n) for (int k = 0; k < 2; ++k) \
;       acc[ai][bj][m][n] = __builtin_amdgcn_mfma_f32_16x16x32_bf16(At[m][k], Bq[n][k], acc[ai][bj][m][n], 0, 0, 0); \
;     __builtin_amdgcn_s_setprio(0); } while (0)
; #define WAIT_V(n) asm volatile("s_waitcnt vmcnt(" #n ")" ::: "memory")
; #define WAIT_L(n) asm volatile("s_waitcnt lgkmcnt(" #n ")" ::: "memory")
; #define BAR __builtin_amdgcn_s_barrier()
; #define SCHED __builtin_amdgcn_sched_barrier(0)
; template <class Epi>
; __device__ __forceinline__ void gemm_tile(const u16* __restrict__ A, const u16* __restrict__ Bt, int K,
;                                           int brow, int bcol, bool first, bool has_next, int nbrow, int nbcol, Epi epi) {
;     ...
;     LDA(At, 1, 1); STAGE(SA(1, 0), A, brow, t + 3);
;     BAR; WAIT_L(0); MMA(1, 0, At, B0); BAR; SCHED;
;     STAGE(SB(1, 1), Bt, bcol + HALF, t + 3);
;     WAIT_V(6); BAR; MMA(1, 1, At, B1); BAR;
;   }
;   { LDB(B0, 0, 0); LDA(At, 0, 0); STAGE(SA(1, 1), A, brow + HALF, nt - 1);
;     BAR; WAIT_L(0); MMA(0, 0, At, B0); BAR;
;     LDB(B1, 0, 1); BAR; WAIT_L(0); MMA(0, 1, At, B1); BAR;
	ds_read_b128 v[196:199], v165 offset:49152
	ds_read_b128 v[200:203], v165 offset:50176
	ds_read_b128 v[204:207], v164 offset:49152
	ds_read_b128 v[208:211], v164 offset:50176
	ds_read_b128 v[212:215], v163 offset:49152
	ds_read_b128 v[216:219], v163 offset:50176
	ds_read_b128 v[220:223], v162 offset:49152
	ds_read_b128 v[240:243], v162 offset:50176
	global_load_lds_dwordx4 v[176:177], off
	v_lshl_add_u64 v[176:177], v[250:251], 0, s[16:17]
	s_mov_b32 m0, s21
	s_nop 0
	global_load_lds_dwordx4 v[176:177], off
	s_barrier
	s_waitcnt lgkmcnt(0)
	s_setprio 1
	s_waitcnt lgkmcnt(0)
	s_nop 0
	v_mfma_f32_16x16x32_bf16 v[60:63], v[196:199], v[180:183], v[60:63]
	v_mfma_f32_16x16x32_bf16 v[56:59], v[196:199], v[188:191], v[56:59]
	v_mfma_f32_16x16x32_bf16 v[52:55], v[204:207], v[180:183], v[52:55]
	v_mfma_f32_16x16x32_bf16 v[48:51], v[204:207], v[188:191], v[48:51]
	v_mfma_f32_16x16x32_bf16 v[44:47], v[212:215], v[180:183], v[44:47]
	v_mfma_f32_16x16x32_bf16 v[40:43], v[212:215], v[188:191], v[40:43]
	v_mfma_f32_16x16x32_bf16 v[36:39], v[220:223], v[180:183], v[36:39]
	v_mfma_f32_16x16x32_bf16 v[32:35], v[220:223], v[188:191], v[32:35]
	v_mfma_f32_16x16x32_bf16 v[60:63], v[200:203], v[184:187], v[60:63]
	v_mfma_f32_16x16x32_bf16 v[56:59], v[200:203], v[192:195], v[56:59]
	v_mfma_f32_16x16x32_bf16 v[52:55], v[208:211], v[184:187], v[52:55]
	v_mfma_f32_16x16x32_bf16 v[48:51], v[208:211], v[192:195], v[48:51]
	v_mfma_f32_16x16x32_bf16 v[44:47], v[216:219], v[184:187], v[44:47]
	v_mfma_f32_16x16x32_bf16 v[40:43], v[216:219], v[192:195], v[40:43]
	v_mfma_f32_16x16x32_bf16 v[36:39], v[240:243], v[184:187], v[36:39]
	v_mfma_f32_16x16x32_bf16 v[32:35], v[240:243], v[192:195], v[32:35]
	s_setprio 0
	s_barrier
	v_add_u32_e32 v176, s85, v161
	v_add_u32_e32 v177, 0x2000, v176
	v_readfirstlane_b32 s21, v176
	v_lshl_add_u64 v[180:181], v[252:253], 0, s[14:15]
	s_mov_b32 m0, s21
	v_readfirstlane_b32 s21, v177
	global_load_lds_dwordx4 v[180:181], off
	v_lshl_add_u64 v[152:153], v[152:153], 0, s[14:15]
	s_mov_b32 m0, s21
	s_nop 0
	global_load_lds_dwordx4 v[152:153], off
	s_waitcnt vmcnt(6)
	s_barrier
	s_setprio 1
	s_nop 0
	v_mfma_f32_16x16x32_bf16 v[28:31], v[196:199], v[224:227], v[28:31]
	v_mfma_f32_16x16x32_bf16 v[24:27], v[196:199], v[232:235], v[24:27]
	v_mfma_f32_16x16x32_bf16 v[20:23], v[204:207], v[224:227], v[20:23]
	v_mfma_f32_16x16x32_bf16 v[16:19], v[204:207], v[232:235], v[16:19]
	v_mfma_f32_16x16x32_bf16 v[12:15], v[212:215], v[224:227], v[12:15]
	v_mfma_f32_16x16x32_bf16 v[8:11], v[212:215], v[232:235], v[8:11]
	v_mfma_f32_16x16x32_bf16 v[4:7], v[220:223], v[224:227], v[4:7]
	v_mfma_f32_16x16x32_bf16 v[0:3], v[220:223], v[232:235], v[0:3]
	v_mfma_f32_16x16x32_bf16 v[28:31], v[200:203], v[228:231], v[28:31]
	v_mfma_f32_16x16x32_bf16 v[24:27], v[200:203], v[236:239], v[24:27]
	v_mfma_f32_16x16x32_bf16 v[20:23], v[208:211], v[228:231], v[20:23]
	v_mfma_f32_16x16x32_bf16 v[16:19], v[208:211], v[236:239], v[16:19]
	v_mfma_f32_16x16x32_bf16 v[12:15], v[216:219], v[228:231], v[12:15]
	v_mfma_f32_16x16x32_bf16 v[8:11], v[216:219], v[236:239], v[8:11]
	v_mfma_f32_16x16x32_bf16 v[4:7], v[240:243], v[228:231], v[4:7]
	v_mfma_f32_16x16x32_bf16 v[0:3], v[240:243], v[236:239], v[0:3]
	s_setprio 0
	s_add_i32 s20, s20, 2
	s_add_u32 s18, s18, 0x100
	s_addc_u32 s19, s19, 0
	s_cmp_lt_u32 s20, 40
	s_barrier
	s_cbranch_scc1 .LBB0_663
	s_add_u32 s2, s34, s2
	s_addc_u32 s3, s35, s3
	s_add_u32 s2, s2, 0x1580
	s_addc_u32 s3, s3, 0
	v_readfirstlane_b32 s18, v178
	v_lshl_add_u64 v[152:153], s[2:3], 0, v[132:133]
	s_mov_b32 m0, s18
	ds_read_b128 v[136:139], v169
	ds_read_b128 v[140:143], v169 offset:1024
	ds_read_b128 v[144:147], v169 offset:2048
	ds_read_b128 v[148:151], v169 offset:3072
	ds_read_b128 v[180:183], v165
	ds_read_b128 v[184:187], v165 offset:1024
	ds_read_b128 v[188:191], v164
	ds_read_b128 v[192:195], v164 offset:1024
	ds_read_b128 v[196:199], v163
	ds_read_b128 v[200:203], v163 offset:1024
	ds_read_b128 v[204:207], v162
	ds_read_b128 v[208:211], v162 offset:1024
	global_load_lds_dwordx4 v[152:153], off
	v_lshl_add_u64 v[152:153], s[2:3], 0, v[134:135]
	v_readfirstlane_b32 s2, v179
	s_mov_b32 m0, s2
	s_nop 0
	global_load_lds_dwordx4 v[152:153], off
	s_barrier
	s_waitcnt lgkmcnt(0)
	s_setprio 1
	s_waitcnt lgkmcnt(0)
	v_mfma_f32_16x16x32_bf16 v[124:127], v[180:183], v[136:139], v[124:127]
	v_mfma_f32_16x16x32_bf16 v[120:123], v[180:183], v[144:147], v[120:123]
	v_mfma_f32_16x16x32_bf16 v[108:111], v[196:199], v[136:139], v[108:111]
	v_mfma_f32_16x16x32_bf16 v[104:107], v[196:199], v[144:147], v[104:107]
	v_mfma_f32_16x16x32_bf16 v[124:127], v[184:187], v[140:143], v[124:127]
	v_mfma_f32_16x16x32_bf16 v[120:123], v[184:187], v[148:151], v[120:123]
	v_mfma_f32_16x16x32_bf16 v[116:119], v[188:191], v[136:139], v[116:119]
	v_mfma_f32_16x16x32_bf16 v[112:115], v[188:191], v[144:147], v[112:115]
	v_mfma_f32_16x16x32_bf16 v[108:111], v[200:203], v[140:143], v[108:111]
	v_mfma_f32_16x16x32_bf16 v[104:107], v[200:203], v[148:151], v[104:107]
	v_mfma_f32_16x16x32_bf16 v[100:103], v[204:207], v[136:139], v[100:103]
	v_mfma_f32_16x16x32_bf16 v[96:99], v[204:207], v[144:147], v[96:99]
	v_mfma_f32_16x16x32_bf16 v[212:215], v[192:195], v[140:143], v[116:119]
	v_mfma_f32_16x16x32_bf16 v[216:219], v[192:195], v[148:151], v[112:115]
	v_mfma_f32_16x16x32_bf16 v[220:223], v[208:211], v[140:143], v[100:103]
	v_mfma_f32_16x16x32_bf16 v[224:227], v[208:211], v[148:151], v[96:99]
	s_setprio 0
	s_barrier
	s_nop 1
	ds_read_b128 v[96:99], v168
	ds_read_b128 v[100:103], v168 offset:1024
	ds_read_b128 v[112:115], v168 offset:2048
	ds_read_b128 v[116:119], v168 offset:3072
	s_barrier
; #define LDA(dst, b, h) for (int m = 0; m < 4; ++m) for (int k = 0; k < 2; ++k) \
;     dst[m][k] = *reinterpret_cast<const bf16x8*>((char*)SA(b, h) + lds_byte(wr * 64 + m * 16 + fr, k * 32 + fq * 8))
; #define LDB(dst, b, h) for (int n = 0; n < 2; ++n) for (int k = 0; k < 2; ++k) \
;     dst[n][k] = *reinterpret_cast<const bf16x8*>((char*)SB(b, h) + lds_byte(wc * 32 + n * 16 + fr, k * 32 + fq * 8))
; #define MMA(ai, bj, At, Bq) do { __builtin_amdgcn_s_setprio(1); \
;     for (int m = 0; m < 4; ++m) for (int n = 0; n < 2; ++n) for (int k = 0; k < 2; ++k) \
;       acc[ai][bj][m][n] = __builtin_amdgcn_mfma_f32_16x16x32_bf16(At[m][k], Bq[n][k], acc[ai][bj][m][n], 0, 0, 0); \
;     __builtin_amdgcn_s_setprio(0); } while (0)
; #define WAIT_V(n) asm volatile("s_waitcnt vmcnt(" #n ")" ::: "memory")
; #define WAIT_L(n) asm volatile("s_waitcnt lgkmcnt(" #n ")" ::: "memory")
; #define BAR __builtin_amdgcn_s_barrier()
; template <class Epi>
; __device__ __forceinline__ void gemm_tile(const u16* __restrict__ A, const u16* __restrict__ Bt, int K,
;                                           int brow, int bcol, bool first, bool has_next, int nbrow, int nbcol, Epi epi) {
;     ...
;     LDB(B1, 0, 1); BAR; WAIT_L(0); MMA(0, 1, At, B1); BAR;
;     LDA(At, 0, 1); WAIT_V(4); BAR; WAIT_L(0); MMA(1, 0, At, B0); MMA(1, 1, At, B1); BAR; }
;   { LDB(B0, 1, 0); LDA(At, 1, 0); WAIT_V(2); BAR; WAIT_L(0); MMA(0, 0, At, B0); BAR;
	s_waitcnt lgkmcnt(0)
	s_setprio 1
	s_waitcnt lgkmcnt(0)
	v_mfma_f32_16x16x32_bf16 v[92:95], v[180:183], v[96:99], v[92:95]
	v_mfma_f32_16x16x32_bf16 v[88:91], v[180:183], v[112:115], v[88:91]
	v_mfma_f32_16x16x32_bf16 v[76:79], v[196:199], v[96:99], v[76:79]
	v_mfma_f32_16x16x32_bf16 v[72:75], v[196:199], v[112:115], v[72:75]
	v_mfma_f32_16x16x32_bf16 v[92:95], v[184:187], v[100:103], v[92:95]
	v_mfma_f32_16x16x32_bf16 v[88:91], v[184:187], v[116:119], v[88:91]
	v_mfma_f32_16x16x32_bf16 v[84:87], v[188:191], v[96:99], v[84:87]
	v_mfma_f32_16x16x32_bf16 v[80:83], v[188:191], v[112:115], v[80:83]
	v_mfma_f32_16x16x32_bf16 v[76:79], v[200:203], v[100:103], v[76:79]
	v_mfma_f32_16x16x32_bf16 v[72:75], v[200:203], v[116:119], v[72:75]
	v_mfma_f32_16x16x32_bf16 v[68:71], v[204:207], v[96:99], v[68:71]
	v_mfma_f32_16x16x32_bf16 v[64:67], v[204:207], v[112:115], v[64:67]
	v_mfma_f32_16x16x32_bf16 v[178:181], v[192:195], v[100:103], v[84:87]
	v_mfma_f32_16x16x32_bf16 v[182:185], v[192:195], v[116:119], v[80:83]
	v_mfma_f32_16x16x32_bf16 v[186:189], v[208:211], v[100:103], v[68:71]
	v_mfma_f32_16x16x32_bf16 v[190:193], v[208:211], v[116:119], v[64:67]
	s_setprio 0
	s_barrier
	s_nop 1
	ds_read_b128 v[64:67], v165 offset:16384
	ds_read_b128 v[68:71], v165 offset:17408
	ds_read_b128 v[80:83], v164 offset:16384
	ds_read_b128 v[84:87], v164 offset:17408
	ds_read_b128 v[194:197], v163 offset:16384
	ds_read_b128 v[198:201], v163 offset:17408
	ds_read_b128 v[202:205], v162 offset:16384
	ds_read_b128 v[206:209], v162 offset:17408
	s_waitcnt vmcnt(4)
	s_barrier
	s_waitcnt lgkmcnt(0)
	s_setprio 1
	s_waitcnt lgkmcnt(0)
	v_mfma_f32_16x16x32_bf16 v[60:63], v[64:67], v[136:139], v[60:63]
	v_mfma_f32_16x16x32_bf16 v[56:59], v[64:67], v[144:147], v[56:59]
	v_mfma_f32_16x16x32_bf16 v[44:47], v[194:197], v[136:139], v[44:47]
	v_mfma_f32_16x16x32_bf16 v[40:43], v[194:197], v[144:147], v[40:43]
	v_mfma_f32_16x16x32_bf16 v[60:63], v[68:71], v[140:143], v[60:63]
	v_mfma_f32_16x16x32_bf16 v[56:59], v[68:71], v[148:151], v[56:59]
	v_mfma_f32_16x16x32_bf16 v[52:55], v[80:83], v[136:139], v[52:55]
	v_mfma_f32_16x16x32_bf16 v[48:51], v[80:83], v[144:147], v[48:51]
	v_mfma_f32_16x16x32_bf16 v[44:47], v[198:201], v[140:143], v[44:47]
	v_mfma_f32_16x16x32_bf16 v[40:43], v[198:201], v[148:151], v[40:43]
	v_mfma_f32_16x16x32_bf16 v[36:39], v[202:205], v[136:139], v[36:39]
	v_mfma_f32_16x16x32_bf16 v[32:35], v[202:205], v[144:147], v[32:35]
	v_mfma_f32_16x16x32_bf16 v[228:231], v[84:87], v[140:143], v[52:55]
	v_mfma_f32_16x16x32_bf16 v[232:235], v[84:87], v[148:151], v[48:51]
	v_mfma_f32_16x16x32_bf16 v[136:139], v[206:209], v[140:143], v[36:39]
	v_mfma_f32_16x16x32_bf16 v[140:143], v[206:209], v[148:151], v[32:35]
	s_setprio 0
	s_setprio 1
	v_mfma_f32_16x16x32_bf16 v[28:31], v[64:67], v[96:99], v[28:31]
	v_mfma_f32_16x16x32_bf16 v[24:27], v[64:67], v[112:115], v[24:27]
	v_mfma_f32_16x16x32_bf16 v[12:15], v[194:197], v[96:99], v[12:15]
	v_mfma_f32_16x16x32_bf16 v[8:11], v[194:197], v[112:115], v[8:11]
	v_mfma_f32_16x16x32_bf16 v[28:31], v[68:71], v[100:103], v[28:31]
	v_mfma_f32_16x16x32_bf16 v[24:27], v[68:71], v[116:119], v[24:27]
	v_mfma_f32_16x16x32_bf16 v[20:23], v[80:83], v[96:99], v[20:23]
	v_mfma_f32_16x16x32_bf16 v[16:19], v[80:83], v[112:115], v[16:19]
	v_mfma_f32_16x16x32_bf16 v[12:15], v[198:201], v[100:103], v[12:15]
	v_mfma_f32_16x16x32_bf16 v[8:11], v[198:201], v[116:119], v[8:11]
	v_mfma_f32_16x16x32_bf16 v[4:7], v[202:205], v[96:99], v[4:7]
	v_mfma_f32_16x16x32_bf16 v[0:3], v[202:205], v[112:115], v[0:3]
	v_mfma_f32_16x16x32_bf16 v[144:147], v[84:87], v[100:103], v[20:23]
	v_mfma_f32_16x16x32_bf16 v[148:151], v[84:87], v[116:119], v[16:19]
	v_mfma_f32_16x16x32_bf16 v[194:197], v[206:209], v[100:103], v[4:7]
	v_mfma_f32_16x16x32_bf16 v[198:201], v[206:209], v[116:119], v[0:3]
	s_setprio 0
	s_barrier
	s_nop 1
	ds_read_b128 v[0:3], v167
	ds_read_b128 v[4:7], v167 offset:1024
	ds_read_b128 v[202:205], v167 offset:2048
	ds_read_b128 v[206:209], v167 offset:3072
	ds_read_b128 v[16:19], v165 offset:32768
	ds_read_b128 v[20:23], v165 offset:33792
	ds_read_b128 v[32:35], v164 offset:32768
	ds_read_b128 v[36:39], v164 offset:33792
	ds_read_b128 v[48:51], v163 offset:32768
	ds_read_b128 v[52:55], v163 offset:33792
	ds_read_b128 v[236:239], v162 offset:32768
	ds_read_b128 v[240:243], v162 offset:33792
	s_waitcnt vmcnt(2)
	s_barrier
; #define LDA(dst, b, h) for (int m = 0; m < 4; ++m) for (int k = 0; k < 2; ++k) \
;     dst[m][k] = *reinterpret_cast<const bf16x8*>((char*)SA(b, h) + lds_byte(wr * 64 + m * 16 + fr, k * 32 + fq * 8))
; #define LDB(dst, b, h) for (int n = 0; n < 2; ++n) for (int k = 0; k < 2; ++k) \
;     dst[n][k] = *reinterpret_cast<const bf16x8*>((char*)SB(b, h) + lds_byte(wc * 32 + n * 16 + fr, k * 32 + fq * 8))
; #define MMA(ai, bj, At, Bq) do { __builtin_amdgcn_s_setprio(1); \
;     for (int m = 0; m < 4; ++m) for (int n = 0; n < 2; ++n) for (int k = 0; k < 2; ++k) \
;       acc[ai][bj][m][n] = __builtin_amdgcn_mfma_f32_16x16x32_bf16(At[m][k], Bq[n][k], acc[ai][bj][m][n], 0, 0, 0); \
;     __builtin_amdgcn_s_setprio(0); } while (0)
; #define WAIT_V(n) asm volatile("s_waitcnt vmcnt(" #n ")" ::: "memory")
; #define WAIT_L(n) asm volatile("s_waitcnt lgkmcnt(" #n ")" ::: "memory")
; #define BAR __builtin_amdgcn_s_barrier()
; template <class Epi>
; __device__ __forceinline__ void gemm_tile(const u16* __restrict__ A, const u16* __restrict__ Bt, int K,
;                                           int brow, int bcol, bool first, bool has_next, int nbrow, int nbcol, Epi epi) {
;     ...
;   { LDB(B0, 1, 0); LDA(At, 1, 0); WAIT_V(2); BAR; WAIT_L(0); MMA(0, 0, At, B0); BAR;
;     LDB(B1, 1, 1); WAIT_V(0); BAR; WAIT_L(0); MMA(0, 1, At, B1); BAR;
;     LDA(At, 1, 1); BAR; WAIT_L(0); MMA(1, 0, At, B0); MMA(1, 1, At, B1); BAR; }
;   if (wr == 0) BAR;
	s_waitcnt lgkmcnt(0)
	s_setprio 1
	s_waitcnt lgkmcnt(0)
	v_mfma_f32_16x16x32_bf16 v[64:67], v[16:19], v[0:3], v[124:127]
	v_mfma_f32_16x16x32_bf16 v[112:115], v[20:23], v[4:7], v[64:67]
	v_mfma_f32_16x16x32_bf16 v[64:67], v[16:19], v[202:205], v[120:123]
	v_mfma_f32_16x16x32_bf16 v[116:119], v[20:23], v[206:209], v[64:67]
	v_mfma_f32_16x16x32_bf16 v[64:67], v[32:35], v[0:3], v[212:215]
	v_mfma_f32_16x16x32_bf16 v[96:99], v[36:39], v[4:7], v[64:67]
	v_mfma_f32_16x16x32_bf16 v[64:67], v[32:35], v[202:205], v[216:219]
	v_mfma_f32_16x16x32_bf16 v[100:103], v[36:39], v[206:209], v[64:67]
	v_mfma_f32_16x16x32_bf16 v[64:67], v[48:51], v[0:3], v[108:111]
	v_mfma_f32_16x16x32_bf16 v[80:83], v[52:55], v[4:7], v[64:67]
	v_mfma_f32_16x16x32_bf16 v[64:67], v[48:51], v[202:205], v[104:107]
	v_mfma_f32_16x16x32_bf16 v[84:87], v[52:55], v[206:209], v[64:67]
	v_mfma_f32_16x16x32_bf16 v[64:67], v[236:239], v[0:3], v[220:223]
	v_mfma_f32_16x16x32_bf16 v[68:71], v[236:239], v[202:205], v[224:227]
	v_mfma_f32_16x16x32_bf16 v[64:67], v[240:243], v[4:7], v[64:67]
	v_mfma_f32_16x16x32_bf16 v[68:71], v[240:243], v[206:209], v[68:71]
	s_setprio 0
	s_barrier
	ds_read_b128 v[210:213], v166
	ds_read_b128 v[214:217], v166 offset:1024
	ds_read_b128 v[218:221], v166 offset:2048
	ds_read_b128 v[166:169], v166 offset:3072
	s_waitcnt vmcnt(0)
	s_barrier
	s_waitcnt lgkmcnt(0)
	s_setprio 1
	s_waitcnt lgkmcnt(0)
	v_mfma_f32_16x16x32_bf16 v[92:95], v[16:19], v[210:213], v[92:95]
	v_mfma_f32_16x16x32_bf16 v[16:19], v[16:19], v[218:221], v[88:91]
	v_mfma_f32_16x16x32_bf16 v[120:123], v[20:23], v[166:169], v[16:19]
	v_mfma_f32_16x16x32_bf16 v[16:19], v[32:35], v[210:213], v[178:181]
	v_mfma_f32_16x16x32_bf16 v[108:111], v[36:39], v[214:217], v[16:19]
	v_mfma_f32_16x16x32_bf16 v[16:19], v[32:35], v[218:221], v[182:185]
	v_mfma_f32_16x16x32_bf16 v[104:107], v[36:39], v[166:169], v[16:19]
	v_mfma_f32_16x16x32_bf16 v[16:19], v[48:51], v[210:213], v[76:79]
	v_mfma_f32_16x16x32_bf16 v[124:127], v[20:23], v[214:217], v[92:95]
	v_mfma_f32_16x16x32_bf16 v[92:95], v[52:55], v[214:217], v[16:19]
	v_mfma_f32_16x16x32_bf16 v[16:19], v[48:51], v[218:221], v[72:75]
	v_mfma_f32_16x16x32_bf16 v[88:91], v[52:55], v[166:169], v[16:19]
	v_mfma_f32_16x16x32_bf16 v[16:19], v[236:239], v[210:213], v[186:189]
	v_mfma_f32_16x16x32_bf16 v[76:79], v[240:243], v[214:217], v[16:19]
	v_mfma_f32_16x16x32_bf16 v[16:19], v[236:239], v[218:221], v[190:193]
	v_mfma_f32_16x16x32_bf16 v[72:75], v[240:243], v[166:169], v[16:19]
	s_setprio 0
	s_barrier
	ds_read_b128 v[178:181], v165 offset:49152
	ds_read_b128 v[182:185], v165 offset:50176
	ds_read_b128 v[186:189], v164 offset:49152
	ds_read_b128 v[190:193], v164 offset:50176
	ds_read_b128 v[222:225], v163 offset:49152
	ds_read_b128 v[236:239], v163 offset:50176
	ds_read_b128 v[240:243], v162 offset:49152
	ds_read_b128 v[162:165], v162 offset:50176
	s_barrier
	s_waitcnt lgkmcnt(0)
	s_setprio 1
	s_waitcnt lgkmcnt(0)
	v_mfma_f32_16x16x32_bf16 v[16:19], v[178:181], v[0:3], v[60:63]
	v_mfma_f32_16x16x32_bf16 v[48:51], v[182:185], v[4:7], v[16:19]
	v_mfma_f32_16x16x32_bf16 v[16:19], v[178:181], v[202:205], v[56:59]
	v_mfma_f32_16x16x32_bf16 v[52:55], v[182:185], v[206:209], v[16:19]
	v_mfma_f32_16x16x32_bf16 v[16:19], v[186:189], v[0:3], v[228:231]
	v_mfma_f32_16x16x32_bf16 v[32:35], v[190:193], v[4:7], v[16:19]
	v_mfma_f32_16x16x32_bf16 v[16:19], v[186:189], v[202:205], v[232:235]
	v_mfma_f32_16x16x32_bf16 v[36:39], v[190:193], v[206:209], v[16:19]
	v_mfma_f32_16x16x32_bf16 v[16:19], v[222:225], v[0:3], v[44:47]
	v_mfma_f32_16x16x32_bf16 v[0:3], v[240:243], v[0:3], v[136:139]
	v_mfma_f32_16x16x32_bf16 v[16:19], v[236:239], v[4:7], v[16:19]
	v_mfma_f32_16x16x32_bf16 v[20:23], v[222:225], v[202:205], v[40:43]
	v_mfma_f32_16x16x32_bf16 v[0:3], v[162:165], v[4:7], v[0:3]
	v_mfma_f32_16x16x32_bf16 v[4:7], v[240:243], v[202:205], v[140:143]
	v_mfma_f32_16x16x32_bf16 v[20:23], v[236:239], v[206:209], v[20:23]
	v_mfma_f32_16x16x32_bf16 v[4:7], v[162:165], v[206:209], v[4:7]
	s_setprio 0
	s_setprio 1
	v_mfma_f32_16x16x32_bf16 v[24:27], v[178:181], v[218:221], v[24:27]
	v_mfma_f32_16x16x32_bf16 v[56:59], v[182:185], v[166:169], v[24:27]
	v_mfma_f32_16x16x32_bf16 v[24:27], v[186:189], v[210:213], v[144:147]
	v_mfma_f32_16x16x32_bf16 v[44:47], v[190:193], v[214:217], v[24:27]
	v_mfma_f32_16x16x32_bf16 v[24:27], v[186:189], v[218:221], v[148:151]
	v_mfma_f32_16x16x32_bf16 v[8:11], v[222:225], v[218:221], v[8:11]
	v_mfma_f32_16x16x32_bf16 v[28:31], v[178:181], v[210:213], v[28:31]
	v_mfma_f32_16x16x32_bf16 v[40:43], v[190:193], v[166:169], v[24:27]
	v_mfma_f32_16x16x32_bf16 v[12:15], v[222:225], v[210:213], v[12:15]
	v_mfma_f32_16x16x32_bf16 v[24:27], v[236:239], v[166:169], v[8:11]
	v_mfma_f32_16x16x32_bf16 v[8:11], v[240:243], v[210:213], v[194:197]
	v_mfma_f32_16x16x32_bf16 v[60:63], v[182:185], v[214:217], v[28:31]
	v_mfma_f32_16x16x32_bf16 v[28:31], v[236:239], v[214:217], v[12:15]
	v_mfma_f32_16x16x32_bf16 v[12:15], v[162:165], v[214:217], v[8:11]
	v_mfma_f32_16x16x32_bf16 v[8:11], v[240:243], v[218:221], v[198:201]
	v_mfma_f32_16x16x32_bf16 v[8:11], v[162:165], v[166:169], v[8:11]
	s_setprio 0
	v_cmp_gt_u32_e32 vcc, s42, v129
	s_barrier
	s_and_saveexec_b64 s[2:3], vcc
	s_cbranch_execz .LBB0_666
	s_barrier
